# asymmetric vmcnt waits: leading wave-half waits for its LDS-DMAs one segment later (end of MFMA segment)
# baseline (speedup 1.0000x reference)
.LBB0_119:
	v_bfe_i32 v2, v0, 27, 1
	v_lshlrev_b32_e32 v4, 4, v0
	v_lshrrev_b32_e32 v2, 22, v2
	v_add_u32_e32 v2, v4, v2
	v_and_b32_e32 v2, 0xfffffc00, v2
	v_sub_u32_e32 v2, v4, v2
	s_waitcnt lgkmcnt(0)
	v_lshrrev_b32_e32 v3, 4, v2
	v_bitop3_b32 v3, v3, v2, 32 bitop3:0x6c
	v_ashrrev_i32_e32 v2, 31, v2
	v_lshrrev_b32_e32 v2, 26, v2
	v_ashrrev_i32_e32 v1, 31, v0
	v_add_u32_e32 v2, v3, v2
	v_lshrrev_b32_e32 v1, 26, v1
	v_ashrrev_i32_e32 v2, 6, v2
	v_add_u32_e32 v1, v0, v1
	v_mul_i32_i24_e32 v7, 64, v2
	v_ashrrev_i32_e32 v1, 6, v1
	v_sub_u32_e32 v3, v3, v7
	v_lshlrev_b32_e32 v5, 3, v1
	v_lshlrev_b32_e32 v6, 5, v1
	v_ashrrev_i16_sdwa v3, v226, sext(v3) dst_sel:DWORD dst_unused:UNUSED_PAD src0_sel:DWORD src1_sel:BYTE_0
	v_and_b32_e32 v5, -16, v5
	v_and_b32_e32 v6, 32, v6
	v_bfe_i32 v3, v3, 0, 16
	v_add_u32_e32 v5, v2, v5
	v_and_b32_e32 v9, 3, v2
	s_mov_b32 s9, 0xfffe0
	v_add_lshl_u32 v6, v6, v3, 1
	v_lshlrev_b32_e32 v7, 1, v5
	v_lshrrev_b32_e32 v8, 2, v5
	v_and_or_b32 v9, v5, s9, v9
	v_lshl_add_u32 v128, v5, 12, v6
	v_add_u32_e32 v5, 0x2000, v4
	v_ashrrev_i32_e32 v4, 31, v5
	v_lshrrev_b32_e32 v4, 22, v4
	v_and_b32_e32 v7, 24, v7
	v_and_b32_e32 v8, 4, v8
	v_add_u32_e32 v4, v5, v4
	v_or3_b32 v7, v9, v8, v7
	v_ashrrev_i32_e32 v4, 10, v4
	v_lshl_add_u32 v192, v7, 12, v6
	v_mul_i32_i24_e32 v6, 0x400, v4
	v_sub_u32_e32 v5, v5, v6
	v_lshrrev_b32_e32 v6, 4, v5
	v_bitop3_b32 v6, v6, v5, 32 bitop3:0x6c
	v_lshlrev_b32_e32 v5, 3, v4
	v_and_b32_e32 v7, -16, v5
	v_ashrrev_i32_e32 v5, 31, v6
	v_lshrrev_b32_e32 v5, 26, v5
	v_add_u32_e32 v8, v6, v5
	v_ashrrev_i32_e32 v5, 6, v8
	v_and_b32_e32 v8, 0xc0, v8
	s_ashr_i32 s0, s36, 6
	v_add_u32_e32 v7, v5, v7
	v_sub_u32_e32 v6, v6, v8
	v_lshlrev_b32_e32 v9, 5, v4
	v_ashrrev_i16_sdwa v6, v226, sext(v6) dst_sel:DWORD dst_unused:UNUSED_PAD src0_sel:DWORD src1_sel:BYTE_0
	v_lshlrev_b32_e32 v8, 1, v7
	v_lshrrev_b32_e32 v10, 2, v7
	v_and_b32_e32 v11, 3, v5
	s_lshl_b32 s39, s0, 10
	v_and_b32_e32 v9, 32, v9
	v_bfe_i32 v6, v6, 0, 16
	v_and_b32_e32 v8, 24, v8
	v_and_b32_e32 v10, 4, v10
	v_and_or_b32 v11, v7, s9, v11
	s_add_i32 s40, s39, 0
	v_or3_b32 v8, v11, v10, v8
	v_add_lshl_u32 v9, v9, v6, 1
	s_add_i32 m0, s40, 0x10000
	v_lshl_add_u32 v132, v8, 12, v9
	global_load_lds_dwordx4 v192, s[4:5]
	s_add_i32 m0, s40, 0x12000
	s_ashr_i32 s1, s36, 8
	global_load_lds_dwordx4 v132, s[4:5]
	s_mov_b32 m0, s40
	s_add_i32 s41, s40, 0x2000
	v_lshl_add_u32 v130, v7, 12, v9
	global_load_lds_dwordx4 v128, s[2:3]
	s_mov_b32 m0, s41
	s_add_u32 s12, s4, 0x80000
	global_load_lds_dwordx4 v130, s[2:3]
	s_addc_u32 s13, s5, 0
	s_add_i32 m0, s40, 0x14000
	v_lshl_add_u64 v[8:9], s[4:5], 0, v[192:193]
	global_load_lds_dwordx4 v192, s[12:13]
	s_add_i32 m0, s40, 0x16000
	v_mov_b32_e32 v133, v193
	global_load_lds_dwordx4 v132, s[12:13]
	s_add_u32 s12, s2, 0x80000
	s_addc_u32 s13, s3, 0
	s_add_i32 s48, s40, 0x4000
	s_mov_b32 m0, s48
	s_add_i32 s49, s40, 0x6000
	global_load_lds_dwordx4 v128, s[12:13]
	s_mov_b32 m0, s49
	v_lshl_add_u64 v[10:11], s[4:5], 0, v[132:133]
	v_mov_b32_e32 v129, v193
	global_load_lds_dwordx4 v130, s[12:13]
	s_add_i32 m0, s40, 0x18000
	v_lshl_add_u64 v[8:9], v[8:9], 0, s[72:73]
	v_lshl_add_u64 v[12:13], s[2:3], 0, v[128:129]
	v_mov_b32_e32 v131, v193
	global_load_lds_dwordx4 v[8:9], off
	v_lshl_add_u64 v[8:9], v[10:11], 0, s[72:73]
	s_add_i32 m0, s40, 0x1a000
	s_add_i32 s50, s40, 0x8000
	v_lshl_add_u64 v[14:15], s[2:3], 0, v[130:131]
	global_load_lds_dwordx4 v[8:9], off
	v_lshl_add_u64 v[8:9], v[12:13], 0, s[72:73]
	s_mov_b32 m0, s50
	s_add_i32 s51, s40, 0xa000
	global_load_lds_dwordx4 v[8:9], off
	v_lshl_add_u64 v[8:9], v[14:15], 0, s[72:73]
	s_mov_b32 m0, s51
	s_add_u32 s12, s4, 0x80080
	global_load_lds_dwordx4 v[8:9], off
	s_addc_u32 s13, s5, 0
	s_add_i32 m0, s40, 0x1c000
	s_nop 0
	global_load_lds_dwordx4 v192, s[12:13]
	s_add_i32 m0, s40, 0x1e000
	s_mov_b32 s98, s1
	s_cmp_lg_u32 s1, 1
	global_load_lds_dwordx4 v132, s[12:13]
	s_cbranch_scc1 .LBB0_121
	s_barrier

.LBB0_132:
	v_add_u32_e32 v138, 0x10000, v141
	ds_read_b128 v[144:147], v138
	ds_read_b128 v[148:151], v138 offset:1024
	ds_read_b128 v[152:155], v138 offset:2048
	ds_read_b128 v[156:159], v138 offset:3072
	ds_read_b128 v[160:163], v142
	ds_read_b128 v[164:167], v142 offset:1024
	ds_read_b128 v[168:171], v142 offset:2048
	ds_read_b128 v[172:175], v142 offset:3072
	ds_read_b128 v[176:179], v142 offset:4096
	ds_read_b128 v[180:183], v142 offset:5120
	ds_read_b128 v[184:187], v142 offset:6144
	ds_read_b128 v[188:191], v142 offset:7168
	v_add_u32_e32 v138, 0x14000, v141
	ds_read_b128 v[194:197], v138
	ds_read_b128 v[198:201], v138 offset:1024
	ds_read_b128 v[202:205], v138 offset:2048
	ds_read_b128 v[206:209], v138 offset:3072
	s_add_i32 s71, s4, 2
	s_add_u32 s5, s2, 0xfff80080
	s_addc_u32 s9, s3, -1
	s_add_i32 s46, 0, 0x10000
	s_cmp_eq_u32 s64, s4
	s_cselect_b32 s4, s28, s67
	s_cselect_b32 s35, s13, s9
	s_cselect_b32 s34, s12, s5
	s_cselect_b32 s5, s29, s69
	v_lshl_add_u64 v[138:139], s[2:3], 0, v[134:135]
	s_add_i32 m0, s40, 0xc000
	s_nop 0
	global_load_lds_dwordx4 v[138:139], off
	v_lshl_add_u64 v[138:139], s[2:3], 0, v[136:137]
	s_add_i32 m0, s40, 0xe000
	s_nop 0
	global_load_lds_dwordx4 v[138:139], off
	s_cmp_eq_u32 s98, 0
	s_cbranch_scc1 .Lawa132w1
	s_waitcnt vmcnt(8)
.Lawa132w1:
	s_waitcnt lgkmcnt(0)
	s_barrier
	s_setprio 1
	v_mfma_f32_16x16x32_bf16 v[124:127], v[144:147], v[160:163], v[124:127]
	v_mfma_f32_16x16x32_bf16 v[120:123], v[152:155], v[160:163], v[120:123]
	v_mfma_f32_16x16x32_bf16 v[116:119], v[144:147], v[168:171], v[116:119]
	v_mfma_f32_16x16x32_bf16 v[108:111], v[152:155], v[168:171], v[108:111]
	v_mfma_f32_16x16x32_bf16 v[100:103], v[144:147], v[176:179], v[100:103]
	v_mfma_f32_16x16x32_bf16 v[92:95], v[152:155], v[176:179], v[92:95]
	v_mfma_f32_16x16x32_bf16 v[84:87], v[144:147], v[184:187], v[84:87]
	v_mfma_f32_16x16x32_bf16 v[76:79], v[152:155], v[184:187], v[76:79]
	v_mfma_f32_16x16x32_bf16 v[124:127], v[148:151], v[164:167], v[124:127]
	v_mfma_f32_16x16x32_bf16 v[120:123], v[156:159], v[164:167], v[120:123]
	v_mfma_f32_16x16x32_bf16 v[116:119], v[148:151], v[172:175], v[116:119]
	v_mfma_f32_16x16x32_bf16 v[108:111], v[156:159], v[172:175], v[108:111]
	v_mfma_f32_16x16x32_bf16 v[100:103], v[148:151], v[180:183], v[100:103]
	v_mfma_f32_16x16x32_bf16 v[92:95], v[156:159], v[180:183], v[92:95]
	v_mfma_f32_16x16x32_bf16 v[84:87], v[148:151], v[188:191], v[84:87]
	v_mfma_f32_16x16x32_bf16 v[76:79], v[156:159], v[188:191], v[76:79]
	v_mfma_f32_16x16x32_bf16 v[112:115], v[194:197], v[160:163], v[112:115]
	v_mfma_f32_16x16x32_bf16 v[104:107], v[202:205], v[160:163], v[104:107]
	v_mfma_f32_16x16x32_bf16 v[96:99], v[194:197], v[168:171], v[96:99]
	v_mfma_f32_16x16x32_bf16 v[88:91], v[202:205], v[168:171], v[88:91]
	v_mfma_f32_16x16x32_bf16 v[80:83], v[194:197], v[176:179], v[80:83]
	v_mfma_f32_16x16x32_bf16 v[72:75], v[202:205], v[176:179], v[72:75]
	v_mfma_f32_16x16x32_bf16 v[68:71], v[194:197], v[184:187], v[68:71]
	v_mfma_f32_16x16x32_bf16 v[64:67], v[202:205], v[184:187], v[64:67]
	v_mfma_f32_16x16x32_bf16 v[112:115], v[198:201], v[164:167], v[112:115]
	v_mfma_f32_16x16x32_bf16 v[104:107], v[206:209], v[164:167], v[104:107]
	v_mfma_f32_16x16x32_bf16 v[96:99], v[198:201], v[172:175], v[96:99]
	v_mfma_f32_16x16x32_bf16 v[88:91], v[206:209], v[172:175], v[88:91]
	v_mfma_f32_16x16x32_bf16 v[80:83], v[198:201], v[180:183], v[80:83]
	v_mfma_f32_16x16x32_bf16 v[72:75], v[206:209], v[180:183], v[72:75]
	v_mfma_f32_16x16x32_bf16 v[68:71], v[198:201], v[188:191], v[68:71]
	v_mfma_f32_16x16x32_bf16 v[64:67], v[206:209], v[188:191], v[64:67]
	s_setprio 0
	s_cmp_lg_u32 s98, 0
	s_cbranch_scc1 .Lawa132w2
	s_waitcnt vmcnt(8)
.Lawa132w2:
	s_barrier
	ds_read_b128 v[160:163], v142 offset:16384
	ds_read_b128 v[164:167], v142 offset:17408
	ds_read_b128 v[168:171], v142 offset:18432
	ds_read_b128 v[172:175], v142 offset:19456
	ds_read_b128 v[176:179], v142 offset:20480
	ds_read_b128 v[180:183], v142 offset:21504
	ds_read_b128 v[184:187], v142 offset:22528
	ds_read_b128 v[188:191], v142 offset:23552
	s_add_i32 s9, 0, 0x14000
	s_add_i32 s46, s46, s39
	v_lshl_add_u64 v[138:139], s[4:5], 0, v[192:193]
	s_mov_b32 m0, s46
	v_lshl_add_u64 v[210:211], s[4:5], 0, v[132:133]
	global_load_lds_dwordx4 v[138:139], off
	s_add_i32 m0, s46, 0x2000
	s_nop 0
	global_load_lds_dwordx4 v[210:211], off
	s_mov_b32 m0, s40
	v_lshl_add_u64 v[212:213], s[34:35], 0, v[128:129]
	global_load_lds_dwordx4 v[212:213], off
	v_lshl_add_u64 v[214:215], s[34:35], 0, v[130:131]
	s_mov_b32 m0, s41
	s_nop 0
	global_load_lds_dwordx4 v[214:215], off
	s_add_u32 s46, s4, 0x80000
	s_addc_u32 s47, s5, 0
	s_add_i32 s9, s9, s39
	v_lshl_add_u64 v[218:219], s[46:47], 0, v[192:193]
	s_mov_b32 m0, s9
	s_nop 0
	global_load_lds_dwordx4 v[218:219], off
	v_lshl_add_u64 v[220:221], s[46:47], 0, v[132:133]
	s_add_i32 m0, s9, 0x2000
	s_nop 0
	global_load_lds_dwordx4 v[220:221], off
	s_cmp_eq_u32 s98, 0
	s_cbranch_scc1 .Lawa132w3
	s_waitcnt vmcnt(8)
.Lawa132w3:
	s_waitcnt lgkmcnt(0)
	s_barrier
	s_setprio 1
	v_mfma_f32_16x16x32_bf16 v[60:63], v[144:147], v[160:163], v[60:63]
	v_mfma_f32_16x16x32_bf16 v[56:59], v[152:155], v[160:163], v[56:59]
	v_mfma_f32_16x16x32_bf16 v[52:55], v[144:147], v[168:171], v[52:55]
	v_mfma_f32_16x16x32_bf16 v[44:47], v[152:155], v[168:171], v[44:47]
	v_mfma_f32_16x16x32_bf16 v[36:39], v[144:147], v[176:179], v[36:39]
	v_mfma_f32_16x16x32_bf16 v[28:31], v[152:155], v[176:179], v[28:31]
	v_mfma_f32_16x16x32_bf16 v[20:23], v[144:147], v[184:187], v[20:23]
	v_mfma_f32_16x16x32_bf16 v[12:15], v[152:155], v[184:187], v[12:15]
	v_mfma_f32_16x16x32_bf16 v[60:63], v[148:151], v[164:167], v[60:63]
	v_mfma_f32_16x16x32_bf16 v[56:59], v[156:159], v[164:167], v[56:59]
	v_mfma_f32_16x16x32_bf16 v[52:55], v[148:151], v[172:175], v[52:55]
	v_mfma_f32_16x16x32_bf16 v[44:47], v[156:159], v[172:175], v[44:47]
	v_mfma_f32_16x16x32_bf16 v[36:39], v[148:151], v[180:183], v[36:39]
	v_mfma_f32_16x16x32_bf16 v[28:31], v[156:159], v[180:183], v[28:31]
	v_mfma_f32_16x16x32_bf16 v[20:23], v[148:151], v[188:191], v[20:23]
	v_mfma_f32_16x16x32_bf16 v[12:15], v[156:159], v[188:191], v[12:15]
	v_mfma_f32_16x16x32_bf16 v[48:51], v[194:197], v[160:163], v[48:51]
	v_mfma_f32_16x16x32_bf16 v[40:43], v[202:205], v[160:163], v[40:43]
	v_mfma_f32_16x16x32_bf16 v[32:35], v[194:197], v[168:171], v[32:35]
	v_mfma_f32_16x16x32_bf16 v[24:27], v[202:205], v[168:171], v[24:27]
	v_mfma_f32_16x16x32_bf16 v[16:19], v[194:197], v[176:179], v[16:19]
	v_mfma_f32_16x16x32_bf16 v[8:11], v[202:205], v[176:179], v[8:11]
	v_mfma_f32_16x16x32_bf16 v[4:7], v[194:197], v[184:187], v[4:7]
	v_mfma_f32_16x16x32_bf16 v[0:3], v[202:205], v[184:187], v[0:3]
	v_mfma_f32_16x16x32_bf16 v[48:51], v[198:201], v[164:167], v[48:51]
	v_mfma_f32_16x16x32_bf16 v[40:43], v[206:209], v[164:167], v[40:43]
	v_mfma_f32_16x16x32_bf16 v[32:35], v[198:201], v[172:175], v[32:35]
	v_mfma_f32_16x16x32_bf16 v[24:27], v[206:209], v[172:175], v[24:27]
	v_mfma_f32_16x16x32_bf16 v[16:19], v[198:201], v[180:183], v[16:19]
	v_mfma_f32_16x16x32_bf16 v[8:11], v[206:209], v[180:183], v[8:11]
	v_mfma_f32_16x16x32_bf16 v[4:7], v[198:201], v[188:191], v[4:7]
	v_mfma_f32_16x16x32_bf16 v[0:3], v[206:209], v[188:191], v[0:3]
	s_setprio 0
	s_cmp_lg_u32 s98, 0
	s_cbranch_scc1 .Lawa132w4
	s_waitcnt vmcnt(8)
.Lawa132w4:
	s_barrier
	v_add_u32_e32 v143, 0x18000, v141
	ds_read_b128 v[144:147], v143
	ds_read_b128 v[148:151], v143 offset:1024
	ds_read_b128 v[152:155], v143 offset:2048
	ds_read_b128 v[156:159], v143 offset:3072
	ds_read_b128 v[160:163], v142 offset:32768
	ds_read_b128 v[164:167], v142 offset:33792
	ds_read_b128 v[168:171], v142 offset:34816
	ds_read_b128 v[172:175], v142 offset:35840
	ds_read_b128 v[176:179], v142 offset:36864
	ds_read_b128 v[180:183], v142 offset:37888
	ds_read_b128 v[184:187], v142 offset:38912
	ds_read_b128 v[188:191], v142 offset:39936
	v_add_u32_e32 v143, 0x1c000, v141
	ds_read_b128 v[194:197], v143
	ds_read_b128 v[198:201], v143 offset:1024
	ds_read_b128 v[202:205], v143 offset:2048
	ds_read_b128 v[206:209], v143 offset:3072
	s_add_i32 s9, 0, 0x18000
	s_add_u32 s34, s34, 0x80000
	s_addc_u32 s35, s35, 0
	s_mov_b32 m0, s48
	v_lshl_add_u64 v[218:219], s[34:35], 0, v[128:129]
	global_load_lds_dwordx4 v[218:219], off
	v_lshl_add_u64 v[220:221], s[34:35], 0, v[130:131]
	s_mov_b32 m0, s49
	s_nop 0
	global_load_lds_dwordx4 v[220:221], off
	s_cmp_eq_u32 s98, 0
	s_cbranch_scc1 .Lawa132w5
	s_waitcnt vmcnt(8)

.Lawa132w6:
	s_barrier
	ds_read_b128 v[160:163], v142 offset:49152
	ds_read_b128 v[164:167], v142 offset:50176
	ds_read_b128 v[168:171], v142 offset:51200
	ds_read_b128 v[172:175], v142 offset:52224
	ds_read_b128 v[176:179], v142 offset:53248
	ds_read_b128 v[180:183], v142 offset:54272
	ds_read_b128 v[184:187], v142 offset:55296
	ds_read_b128 v[188:191], v142 offset:56320
	s_add_i32 s34, 0, 0x1c000
	s_add_i32 s9, s9, s39
	v_lshl_add_u64 v[138:139], v[138:139], 0, s[72:73]
	s_mov_b32 m0, s9
	s_nop 0
	global_load_lds_dwordx4 v[138:139], off
	v_lshl_add_u64 v[138:139], v[210:211], 0, s[72:73]
	s_add_i32 m0, s9, 0x2000
	s_nop 0
	global_load_lds_dwordx4 v[138:139], off
	s_mov_b32 m0, s50
	v_lshl_add_u64 v[138:139], v[212:213], 0, s[72:73]
	global_load_lds_dwordx4 v[138:139], off
	v_lshl_add_u64 v[138:139], v[214:215], 0, s[72:73]
	s_mov_b32 m0, s51
	s_nop 0
	global_load_lds_dwordx4 v[138:139], off
	s_add_u32 s4, s4, 0x80080
	s_addc_u32 s5, s5, 0
	s_add_i32 s9, s34, s39
	v_lshl_add_u64 v[138:139], s[4:5], 0, v[192:193]
	s_mov_b32 m0, s9
	s_nop 0
	global_load_lds_dwordx4 v[138:139], off
	v_lshl_add_u64 v[138:139], s[4:5], 0, v[132:133]
	s_add_i32 m0, s9, 0x2000
	s_nop 0
	global_load_lds_dwordx4 v[138:139], off
	s_cmp_eq_u32 s98, 0
	s_cbranch_scc1 .Lawa132w7
	s_waitcnt vmcnt(8)

.Lawa132w8:
	s_add_u32 s2, s2, 0x100
	s_addc_u32 s3, s3, 0
	s_add_u32 s67, s67, 0x100
	s_addc_u32 s69, s69, 0
	s_cmp_ge_i32 s71, s63
	s_mov_b32 s4, s71
	s_barrier
	s_cbranch_scc0 .LBB0_132
	v_sub_co_u32_e64 v138, s[2:3], s66, 1
	s_nop 0
	v_readfirstlane_b32 s64, v138
	s_lshl_b64 s[4:5], s[64:65], 22
	v_readlane_b32 s34, v252, 9
	v_readlane_b32 s35, v252, 10
	s_add_u32 s4, s34, s4
	s_addc_u32 s5, s35, s5
	s_sub_i32 s9, s62, 32
	s_and_b64 s[2:3], s[2:3], exec
	v_readlane_b32 s34, v252, 7
	s_cselect_b32 s2, s62, s9
	v_readlane_b32 s35, v252, 8
	s_cselect_b32 s5, s35, s5
	s_cselect_b32 s4, s34, s4
	s_ashr_i32 s3, s2, 31
	s_lshl_b64 s[2:3], s[2:3], 20
	s_add_u32 s2, s4, s2
	v_mov_b32 v139, v140
	s_addc_u32 s3, s5, s3
	v_ashrrev_i32_e32 v138, 1, v139
	s_lshl_b32 s4, s58, 8
	v_and_b32_e32 v138, -8, v138
	s_or_b32 s4, s4, s53
	v_add_u32_e32 v138, s4, v138
	v_and_or_b32 v144, v139, 15, s52
	v_ashrrev_i32_e32 v139, 31, v138
	v_ashrrev_i32_e32 v145, 31, v144
	v_lshl_add_u64 v[146:147], v[138:139], 1, s[2:3]
	v_lshlrev_b64 v[138:139], 12, v[144:145]
	v_lshl_add_u64 v[138:139], v[146:147], 0, v[138:139]
	v_cvt_pk_bf16_f32 v124, v124, v125
	v_cvt_pk_bf16_f32 v125, v126, v127
	v_cvt_pk_bf16_f32 v126, v120, v121
	v_cvt_pk_bf16_f32 v127, v122, v123
	global_store_dwordx4 v[138:139], v[124:127], off
	v_cvt_pk_bf16_f32 v112, v112, v113
	v_cvt_pk_bf16_f32 v113, v114, v115
	v_cvt_pk_bf16_f32 v114, v104, v105
	v_or_b32_e32 v104, 16, v144
	v_ashrrev_i32_e32 v105, 31, v104
	v_lshlrev_b64 v[104:105], 12, v[104:105]
	v_cvt_pk_bf16_f32 v115, v106, v107
	global_store_dwordx4 v[138:139], v[112:115], off offset:256
	s_mov_b64 s[2:3], 0x80000
	s_mov_b32 s58, s55
	v_lshl_add_u64 v[112:113], v[146:147], 0, v[104:105]
	v_cvt_pk_bf16_f32 v104, v116, v117
	v_cvt_pk_bf16_f32 v105, v118, v119
	v_cvt_pk_bf16_f32 v106, v108, v109
	v_cvt_pk_bf16_f32 v107, v110, v111
	global_store_dwordx4 v[112:113], v[104:107], off
	v_cvt_pk_bf16_f32 v96, v96, v97
	v_cvt_pk_bf16_f32 v97, v98, v99
	v_cvt_pk_bf16_f32 v98, v88, v89
	v_or_b32_e32 v88, 32, v144
	v_ashrrev_i32_e32 v89, 31, v88
	v_lshlrev_b64 v[88:89], 12, v[88:89]
	v_cvt_pk_bf16_f32 v99, v90, v91
	global_store_dwordx4 v[112:113], v[96:99], off offset:256
	s_mov_b32 s62, s14
	s_mov_b32 s66, s15
	v_lshl_add_u64 v[96:97], v[146:147], 0, v[88:89]
	v_cvt_pk_bf16_f32 v88, v100, v101
	v_cvt_pk_bf16_f32 v89, v102, v103
	v_cvt_pk_bf16_f32 v90, v92, v93
	v_cvt_pk_bf16_f32 v91, v94, v95
	global_store_dwordx4 v[96:97], v[88:91], off
	v_cvt_pk_bf16_f32 v80, v80, v81
	v_cvt_pk_bf16_f32 v81, v82, v83
	v_cvt_pk_bf16_f32 v82, v72, v73
	v_or_b32_e32 v72, 48, v144
	v_ashrrev_i32_e32 v73, 31, v72
	v_lshlrev_b64 v[72:73], 12, v[72:73]
	v_cvt_pk_bf16_f32 v83, v74, v75
	global_store_dwordx4 v[96:97], v[80:83], off offset:256
	s_mov_b32 s63, s59
	s_mov_b64 s[4:5], s[28:29]
	v_lshl_add_u64 v[80:81], v[146:147], 0, v[72:73]
	v_cvt_pk_bf16_f32 v72, v84, v85
	v_cvt_pk_bf16_f32 v73, v86, v87
	v_cvt_pk_bf16_f32 v74, v76, v77
	v_cvt_pk_bf16_f32 v75, v78, v79
	global_store_dwordx4 v[80:81], v[72:75], off
	v_cvt_pk_bf16_f32 v68, v68, v69
	v_cvt_pk_bf16_f32 v69, v70, v71
	v_cvt_pk_bf16_f32 v70, v64, v65
	v_lshl_add_u64 v[64:65], v[138:139], 0, s[2:3]
	s_mov_b32 s2, 0x80000
	v_cvt_pk_bf16_f32 v71, v66, v67
	global_store_dwordx4 v[80:81], v[68:71], off offset:256
	v_cvt_pk_bf16_f32 v60, v60, v61
	v_cvt_pk_bf16_f32 v61, v62, v63
	v_cvt_pk_bf16_f32 v62, v56, v57
	v_add_co_u32_e32 v56, vcc, s2, v138
	v_cvt_pk_bf16_f32 v63, v58, v59
	s_mov_b64 s[2:3], 0x90000
	s_nop 0
	v_addc_co_u32_e32 v57, vcc, 0, v139, vcc
	global_store_dwordx4 v[56:57], v[60:63], off
	v_cvt_pk_bf16_f32 v48, v48, v49
	v_cvt_pk_bf16_f32 v49, v50, v51
	v_cvt_pk_bf16_f32 v50, v40, v41
	v_cvt_pk_bf16_f32 v51, v42, v43
	global_store_dwordx4 v[64:65], v[48:51], off offset:256
	v_cvt_pk_bf16_f32 v40, v52, v53
	v_cvt_pk_bf16_f32 v41, v54, v55
	v_cvt_pk_bf16_f32 v42, v44, v45
	v_cvt_pk_bf16_f32 v43, v46, v47
	s_nop 1
	v_lshl_add_u64 v[48:49], v[138:139], 0, s[2:3]
	s_mov_b32 s2, 0x90000
	v_add_co_u32_e32 v44, vcc, s2, v138
	s_mov_b64 s[2:3], 0xa0000
	s_nop 0
	v_addc_co_u32_e32 v45, vcc, 0, v139, vcc
	global_store_dwordx4 v[44:45], v[40:43], off
	v_cvt_pk_bf16_f32 v32, v32, v33
	v_cvt_pk_bf16_f32 v33, v34, v35
	v_cvt_pk_bf16_f32 v34, v24, v25
	v_cvt_pk_bf16_f32 v35, v26, v27
	global_store_dwordx4 v[48:49], v[32:35], off offset:256
	v_cvt_pk_bf16_f32 v24, v36, v37
	v_cvt_pk_bf16_f32 v25, v38, v39
	v_cvt_pk_bf16_f32 v26, v28, v29
	v_cvt_pk_bf16_f32 v27, v30, v31
	s_nop 1
	v_lshl_add_u64 v[32:33], v[138:139], 0, s[2:3]
	s_mov_b32 s2, 0xa0000
	v_add_co_u32_e32 v28, vcc, s2, v138
	s_mov_b64 s[2:3], 0xb0000
	s_nop 0
	v_addc_co_u32_e32 v29, vcc, 0, v139, vcc
	global_store_dwordx4 v[28:29], v[24:27], off
	v_cvt_pk_bf16_f32 v16, v16, v17
	v_cvt_pk_bf16_f32 v17, v18, v19
	v_cvt_pk_bf16_f32 v18, v8, v9
	v_cvt_pk_bf16_f32 v19, v10, v11
	global_store_dwordx4 v[32:33], v[16:19], off offset:256
	v_cvt_pk_bf16_f32 v8, v20, v21
	v_cvt_pk_bf16_f32 v9, v22, v23
	v_cvt_pk_bf16_f32 v10, v12, v13
	v_cvt_pk_bf16_f32 v11, v14, v15
	s_nop 1
	v_lshl_add_u64 v[16:17], v[138:139], 0, s[2:3]
	s_mov_b32 s2, 0xb0000
	v_add_co_u32_e32 v12, vcc, s2, v138
	s_mov_b64 s[2:3], s[12:13]
	s_nop 0
	v_addc_co_u32_e32 v13, vcc, 0, v139, vcc
	s_and_b64 vcc, exec, s[0:1]
	global_store_dwordx4 v[12:13], v[8:11], off
	v_cvt_pk_bf16_f32 v4, v4, v5
	v_cvt_pk_bf16_f32 v5, v6, v7
	v_cvt_pk_bf16_f32 v6, v0, v1
	v_cvt_pk_bf16_f32 v7, v2, v3
	global_store_dwordx4 v[16:17], v[4:7], off offset:256
	s_cbranch_vccz .LBB0_122
	s_waitcnt vmcnt(0)
	s_cmpk_gt_u32 s36, 0xff
	s_cbranch_scc1 .LBB0_136
	s_barrier

.LBB0_229:
	v_bfe_i32 v2, v0, 27, 1
	v_lshlrev_b32_e32 v4, 4, v0
	v_lshrrev_b32_e32 v2, 22, v2
	v_add_u32_e32 v2, v4, v2
	v_and_b32_e32 v2, 0xfffffc00, v2
	v_sub_u32_e32 v2, v4, v2
	s_waitcnt lgkmcnt(0)
	v_lshrrev_b32_e32 v3, 4, v2
	v_bitop3_b32 v3, v3, v2, 32 bitop3:0x6c
	v_ashrrev_i32_e32 v2, 31, v2
	v_lshrrev_b32_e32 v2, 26, v2
	v_ashrrev_i32_e32 v1, 31, v0
	v_add_u32_e32 v2, v3, v2
	v_lshrrev_b32_e32 v1, 26, v1
	v_ashrrev_i32_e32 v2, 6, v2
	v_add_u32_e32 v1, v0, v1
	v_mul_i32_i24_e32 v7, 64, v2
	v_ashrrev_i32_e32 v1, 6, v1
	v_sub_u32_e32 v3, v3, v7
	v_lshlrev_b32_e32 v5, 3, v1
	v_lshlrev_b32_e32 v6, 5, v1
	v_ashrrev_i16_sdwa v3, v226, sext(v3) dst_sel:DWORD dst_unused:UNUSED_PAD src0_sel:DWORD src1_sel:BYTE_0
	v_and_b32_e32 v5, -16, v5
	v_and_b32_e32 v6, 32, v6
	v_bfe_i32 v3, v3, 0, 16
	v_add_u32_e32 v5, v2, v5
	v_and_b32_e32 v9, 3, v2
	s_mov_b32 s9, 0x3ffe0
	v_add_lshl_u32 v6, v6, v3, 1
	v_lshlrev_b32_e32 v7, 1, v5
	v_lshrrev_b32_e32 v8, 2, v5
	v_and_or_b32 v9, v5, s9, v9
	v_lshl_add_u32 v128, v5, 14, v6
	v_add_u32_e32 v5, 0x2000, v4
	v_ashrrev_i32_e32 v4, 31, v5
	v_lshrrev_b32_e32 v4, 22, v4
	v_and_b32_e32 v7, 24, v7
	v_and_b32_e32 v8, 4, v8
	v_add_u32_e32 v4, v5, v4
	v_or3_b32 v7, v9, v8, v7
	v_ashrrev_i32_e32 v4, 10, v4
	v_lshl_add_u32 v192, v7, 14, v6
	v_mul_i32_i24_e32 v6, 0x400, v4
	v_sub_u32_e32 v5, v5, v6
	v_lshrrev_b32_e32 v6, 4, v5
	v_bitop3_b32 v6, v6, v5, 32 bitop3:0x6c
	v_lshlrev_b32_e32 v5, 3, v4
	v_and_b32_e32 v7, -16, v5
	v_ashrrev_i32_e32 v5, 31, v6
	v_lshrrev_b32_e32 v5, 26, v5
	v_add_u32_e32 v8, v6, v5
	v_ashrrev_i32_e32 v5, 6, v8
	v_and_b32_e32 v8, 0xc0, v8
	s_ashr_i32 s14, s40, 6
	v_add_u32_e32 v7, v5, v7
	v_sub_u32_e32 v6, v6, v8
	v_lshlrev_b32_e32 v9, 5, v4
	v_ashrrev_i16_sdwa v6, v226, sext(v6) dst_sel:DWORD dst_unused:UNUSED_PAD src0_sel:DWORD src1_sel:BYTE_0
	v_lshlrev_b32_e32 v8, 1, v7
	v_lshrrev_b32_e32 v10, 2, v7
	v_and_b32_e32 v11, 3, v5
	s_lshl_b32 s49, s14, 10
	v_and_b32_e32 v9, 32, v9
	v_bfe_i32 v6, v6, 0, 16
	v_and_b32_e32 v8, 24, v8
	v_and_b32_e32 v10, 4, v10
	v_and_or_b32 v11, v7, s9, v11
	s_add_i32 s50, s49, 0
	v_or3_b32 v8, v11, v10, v8
	v_add_lshl_u32 v9, v9, v6, 1
	s_add_i32 m0, s50, 0x10000
	v_lshl_add_u32 v132, v8, 14, v9
	global_load_lds_dwordx4 v192, s[4:5]
	s_add_i32 m0, s50, 0x12000
	s_ashr_i32 s15, s40, 8
	global_load_lds_dwordx4 v132, s[4:5]
	s_mov_b32 m0, s50
	s_add_i32 s51, s50, 0x2000
	v_lshl_add_u32 v130, v7, 14, v9
	global_load_lds_dwordx4 v128, s[2:3]
	s_mov_b32 m0, s51
	s_add_u32 s28, s4, 0x200000
	global_load_lds_dwordx4 v130, s[2:3]
	s_addc_u32 s29, s5, 0
	s_add_i32 m0, s50, 0x14000
	v_lshl_add_u64 v[8:9], s[4:5], 0, v[192:193]
	global_load_lds_dwordx4 v192, s[28:29]
	s_add_i32 m0, s50, 0x16000
	v_mov_b32_e32 v133, v193
	global_load_lds_dwordx4 v132, s[28:29]
	s_add_u32 s28, s2, 0x200000
	s_addc_u32 s29, s3, 0
	s_add_i32 s52, s50, 0x4000
	s_mov_b32 m0, s52
	s_add_i32 s53, s50, 0x6000
	global_load_lds_dwordx4 v128, s[28:29]
	s_mov_b32 m0, s53
	v_lshl_add_u64 v[10:11], s[4:5], 0, v[132:133]
	v_mov_b32_e32 v129, v193
	global_load_lds_dwordx4 v130, s[28:29]
	s_add_i32 m0, s50, 0x18000
	v_lshl_add_u64 v[8:9], v[8:9], 0, s[72:73]
	v_lshl_add_u64 v[12:13], s[2:3], 0, v[128:129]
	v_mov_b32_e32 v131, v193
	global_load_lds_dwordx4 v[8:9], off
	v_lshl_add_u64 v[8:9], v[10:11], 0, s[72:73]
	s_add_i32 m0, s50, 0x1a000
	s_add_i32 s54, s50, 0x8000
	v_lshl_add_u64 v[14:15], s[2:3], 0, v[130:131]
	global_load_lds_dwordx4 v[8:9], off
	v_lshl_add_u64 v[8:9], v[12:13], 0, s[72:73]
	s_mov_b32 m0, s54
	s_add_i32 s55, s50, 0xa000
	global_load_lds_dwordx4 v[8:9], off
	v_lshl_add_u64 v[8:9], v[14:15], 0, s[72:73]
	s_mov_b32 m0, s55
	s_add_u32 s28, s4, 0x200080
	global_load_lds_dwordx4 v[8:9], off
	s_addc_u32 s29, s5, 0
	s_add_i32 m0, s50, 0x1c000
	s_nop 0
	global_load_lds_dwordx4 v192, s[28:29]
	s_add_i32 m0, s50, 0x1e000
	s_mov_b32 s98, s15
	s_cmp_lg_u32 s15, 1
	global_load_lds_dwordx4 v132, s[28:29]
	s_cbranch_scc1 .LBB0_231
	s_barrier

.LBB0_242:
	v_add_u32_e32 v138, 0x10000, v141
	ds_read_b128 v[144:147], v138
	ds_read_b128 v[148:151], v138 offset:1024
	ds_read_b128 v[152:155], v138 offset:2048
	ds_read_b128 v[156:159], v138 offset:3072
	ds_read_b128 v[160:163], v142
	ds_read_b128 v[164:167], v142 offset:1024
	ds_read_b128 v[168:171], v142 offset:2048
	ds_read_b128 v[172:175], v142 offset:3072
	ds_read_b128 v[176:179], v142 offset:4096
	ds_read_b128 v[180:183], v142 offset:5120
	ds_read_b128 v[184:187], v142 offset:6144
	ds_read_b128 v[188:191], v142 offset:7168
	v_add_u32_e32 v138, 0x14000, v141
	ds_read_b128 v[194:197], v138
	ds_read_b128 v[198:201], v138 offset:1024
	ds_read_b128 v[202:205], v138 offset:2048
	ds_read_b128 v[206:209], v138 offset:3072
	s_add_i32 s79, s4, 2
	s_add_u32 s5, s2, 0xffe00080
	s_addc_u32 s9, s3, -1
	s_add_i32 s46, 0, 0x10000
	s_cmp_eq_u32 s64, s4
	s_cselect_b32 s4, s36, s75
	s_cselect_b32 s39, s29, s9
	s_cselect_b32 s38, s28, s5
	s_cselect_b32 s5, s37, s78
	v_lshl_add_u64 v[138:139], s[2:3], 0, v[134:135]
	s_add_i32 m0, s50, 0xc000
	s_nop 0
	global_load_lds_dwordx4 v[138:139], off
	v_lshl_add_u64 v[138:139], s[2:3], 0, v[136:137]
	s_add_i32 m0, s50, 0xe000
	s_nop 0
	global_load_lds_dwordx4 v[138:139], off
	s_cmp_eq_u32 s98, 0
	s_cbranch_scc1 .Lawa242w1
	s_waitcnt vmcnt(8)

.Lawa242w2:
	s_barrier
	ds_read_b128 v[160:163], v142 offset:16384
	ds_read_b128 v[164:167], v142 offset:17408
	ds_read_b128 v[168:171], v142 offset:18432
	ds_read_b128 v[172:175], v142 offset:19456
	ds_read_b128 v[176:179], v142 offset:20480
	ds_read_b128 v[180:183], v142 offset:21504
	ds_read_b128 v[184:187], v142 offset:22528
	ds_read_b128 v[188:191], v142 offset:23552
	s_add_i32 s9, 0, 0x14000
	s_add_i32 s46, s46, s49
	v_lshl_add_u64 v[138:139], s[4:5], 0, v[192:193]
	s_mov_b32 m0, s46
	v_lshl_add_u64 v[210:211], s[4:5], 0, v[132:133]
	global_load_lds_dwordx4 v[138:139], off
	s_add_i32 m0, s46, 0x2000
	s_nop 0
	global_load_lds_dwordx4 v[210:211], off
	s_mov_b32 m0, s50
	v_lshl_add_u64 v[212:213], s[38:39], 0, v[128:129]
	global_load_lds_dwordx4 v[212:213], off
	v_lshl_add_u64 v[214:215], s[38:39], 0, v[130:131]
	s_mov_b32 m0, s51
	s_nop 0
	global_load_lds_dwordx4 v[214:215], off
	s_add_u32 s46, s4, 0x200000
	s_addc_u32 s47, s5, 0
	s_add_i32 s9, s9, s49
	v_lshl_add_u64 v[218:219], s[46:47], 0, v[192:193]
	s_mov_b32 m0, s9
	s_nop 0
	global_load_lds_dwordx4 v[218:219], off
	v_lshl_add_u64 v[220:221], s[46:47], 0, v[132:133]
	s_add_i32 m0, s9, 0x2000
	s_nop 0
	global_load_lds_dwordx4 v[220:221], off
	s_cmp_eq_u32 s98, 0
	s_cbranch_scc1 .Lawa242w3
	s_waitcnt vmcnt(8)

.Lawa242w4:
	s_barrier
	v_add_u32_e32 v143, 0x18000, v141
	ds_read_b128 v[144:147], v143
	ds_read_b128 v[148:151], v143 offset:1024
	ds_read_b128 v[152:155], v143 offset:2048
	ds_read_b128 v[156:159], v143 offset:3072
	ds_read_b128 v[160:163], v142 offset:32768
	ds_read_b128 v[164:167], v142 offset:33792
	ds_read_b128 v[168:171], v142 offset:34816
	ds_read_b128 v[172:175], v142 offset:35840
	ds_read_b128 v[176:179], v142 offset:36864
	ds_read_b128 v[180:183], v142 offset:37888
	ds_read_b128 v[184:187], v142 offset:38912
	ds_read_b128 v[188:191], v142 offset:39936
	v_add_u32_e32 v143, 0x1c000, v141
	ds_read_b128 v[194:197], v143
	ds_read_b128 v[198:201], v143 offset:1024
	ds_read_b128 v[202:205], v143 offset:2048
	ds_read_b128 v[206:209], v143 offset:3072
	s_add_i32 s9, 0, 0x18000
	s_add_u32 s38, s38, 0x200000
	s_addc_u32 s39, s39, 0
	s_mov_b32 m0, s52
	v_lshl_add_u64 v[218:219], s[38:39], 0, v[128:129]
	global_load_lds_dwordx4 v[218:219], off
	v_lshl_add_u64 v[220:221], s[38:39], 0, v[130:131]
	s_mov_b32 m0, s53
	s_nop 0
	global_load_lds_dwordx4 v[220:221], off
	s_cmp_eq_u32 s98, 0
	s_cbranch_scc1 .Lawa242w5
	s_waitcnt vmcnt(8)

.Lawa242w6:
	s_barrier
	ds_read_b128 v[160:163], v142 offset:49152
	ds_read_b128 v[164:167], v142 offset:50176
	ds_read_b128 v[168:171], v142 offset:51200
	ds_read_b128 v[172:175], v142 offset:52224
	ds_read_b128 v[176:179], v142 offset:53248
	ds_read_b128 v[180:183], v142 offset:54272
	ds_read_b128 v[184:187], v142 offset:55296
	ds_read_b128 v[188:191], v142 offset:56320
	s_add_i32 s38, 0, 0x1c000
	s_add_i32 s9, s9, s49
	v_lshl_add_u64 v[138:139], v[138:139], 0, s[72:73]
	s_mov_b32 m0, s9
	s_nop 0
	global_load_lds_dwordx4 v[138:139], off
	v_lshl_add_u64 v[138:139], v[210:211], 0, s[72:73]
	s_add_i32 m0, s9, 0x2000
	s_nop 0
	global_load_lds_dwordx4 v[138:139], off
	s_mov_b32 m0, s54
	v_lshl_add_u64 v[138:139], v[212:213], 0, s[72:73]
	global_load_lds_dwordx4 v[138:139], off
	v_lshl_add_u64 v[138:139], v[214:215], 0, s[72:73]
	s_mov_b32 m0, s55
	s_nop 0
	global_load_lds_dwordx4 v[138:139], off
	s_add_u32 s4, s4, 0x200080
	s_addc_u32 s5, s5, 0
	s_add_i32 s9, s38, s49
	v_lshl_add_u64 v[138:139], s[4:5], 0, v[192:193]
	s_mov_b32 m0, s9
	s_nop 0
	global_load_lds_dwordx4 v[138:139], off
	v_lshl_add_u64 v[138:139], s[4:5], 0, v[132:133]
	s_add_i32 m0, s9, 0x2000
	s_nop 0
	global_load_lds_dwordx4 v[138:139], off
	s_cmp_eq_u32 s98, 0
	s_cbranch_scc1 .Lawa242w7
	s_waitcnt vmcnt(8)

.Lawa242w8:
	s_add_u32 s2, s2, 0x100
	s_addc_u32 s3, s3, 0
	s_add_u32 s75, s75, 0x100
	s_addc_u32 s78, s78, 0
	s_cmp_ge_i32 s79, s71
	s_mov_b32 s4, s79
	s_barrier
	s_cbranch_scc0 .LBB0_242
	v_sub_co_u32_e64 v138, s[2:3], s74, 1
	s_nop 0
	v_readfirstlane_b32 s64, v138
	s_lshl_b64 s[4:5], s[64:65], 22
	v_readlane_b32 s38, v252, 9
	v_readlane_b32 s39, v252, 10
	s_add_u32 s4, s38, s4
	s_addc_u32 s5, s39, s5
	s_sub_i32 s9, s69, 32
	s_and_b64 s[2:3], s[2:3], exec
	v_readlane_b32 s38, v252, 7
	s_cselect_b32 s2, s69, s9
	v_readlane_b32 s39, v252, 8
	s_cselect_b32 s5, s39, s5
	s_cselect_b32 s4, s38, s4
	s_ashr_i32 s3, s2, 31
	s_lshl_b64 s[2:3], s[2:3], 20
	s_add_u32 s2, s4, s2
	v_mov_b32 v139, v140
	s_addc_u32 s3, s5, s3
	v_ashrrev_i32_e32 v138, 1, v139
	s_lshl_b32 s4, s66, 8
	v_and_b32_e32 v138, -8, v138
	s_or_b32 s4, s4, s59
	v_add_u32_e32 v138, s4, v138
	v_and_or_b32 v144, v139, 15, s58
	v_ashrrev_i32_e32 v139, 31, v138
	v_ashrrev_i32_e32 v145, 31, v144
	v_lshl_add_u64 v[146:147], v[138:139], 1, s[2:3]
	v_lshlrev_b64 v[138:139], 12, v[144:145]
	v_lshl_add_u64 v[138:139], v[146:147], 0, v[138:139]
	v_cvt_pk_bf16_f32 v124, v124, v125
	v_cvt_pk_bf16_f32 v125, v126, v127
	v_cvt_pk_bf16_f32 v126, v120, v121
	v_cvt_pk_bf16_f32 v127, v122, v123
	global_store_dwordx4 v[138:139], v[124:127], off
	v_cvt_pk_bf16_f32 v112, v112, v113
	v_cvt_pk_bf16_f32 v113, v114, v115
	v_cvt_pk_bf16_f32 v114, v104, v105
	v_or_b32_e32 v104, 16, v144
	v_ashrrev_i32_e32 v105, 31, v104
	v_lshlrev_b64 v[104:105], 12, v[104:105]
	v_cvt_pk_bf16_f32 v115, v106, v107
	global_store_dwordx4 v[138:139], v[112:115], off offset:256
	s_mov_b64 s[2:3], 0x80000
	s_mov_b32 s66, s63
	v_lshl_add_u64 v[112:113], v[146:147], 0, v[104:105]
	v_cvt_pk_bf16_f32 v104, v116, v117
	v_cvt_pk_bf16_f32 v105, v118, v119
	v_cvt_pk_bf16_f32 v106, v108, v109
	v_cvt_pk_bf16_f32 v107, v110, v111
	global_store_dwordx4 v[112:113], v[104:107], off
	v_cvt_pk_bf16_f32 v96, v96, v97
	v_cvt_pk_bf16_f32 v97, v98, v99
	v_cvt_pk_bf16_f32 v98, v88, v89
	v_or_b32_e32 v88, 32, v144
	v_ashrrev_i32_e32 v89, 31, v88
	v_lshlrev_b64 v[88:89], 12, v[88:89]
	v_cvt_pk_bf16_f32 v99, v90, v91
	global_store_dwordx4 v[112:113], v[96:99], off offset:256
	s_mov_b32 s69, s34
	s_mov_b32 s74, s35
	v_lshl_add_u64 v[96:97], v[146:147], 0, v[88:89]
	v_cvt_pk_bf16_f32 v88, v100, v101
	v_cvt_pk_bf16_f32 v89, v102, v103
	v_cvt_pk_bf16_f32 v90, v92, v93
	v_cvt_pk_bf16_f32 v91, v94, v95
	global_store_dwordx4 v[96:97], v[88:91], off
	v_cvt_pk_bf16_f32 v80, v80, v81
	v_cvt_pk_bf16_f32 v81, v82, v83
	v_cvt_pk_bf16_f32 v82, v72, v73
	v_or_b32_e32 v72, 48, v144
	v_ashrrev_i32_e32 v73, 31, v72
	v_lshlrev_b64 v[72:73], 12, v[72:73]
	v_cvt_pk_bf16_f32 v83, v74, v75
	global_store_dwordx4 v[96:97], v[80:83], off offset:256
	s_mov_b32 s71, s67
	s_mov_b64 s[4:5], s[36:37]
	v_lshl_add_u64 v[80:81], v[146:147], 0, v[72:73]
	v_cvt_pk_bf16_f32 v72, v84, v85
	v_cvt_pk_bf16_f32 v73, v86, v87
	v_cvt_pk_bf16_f32 v74, v76, v77
	v_cvt_pk_bf16_f32 v75, v78, v79
	global_store_dwordx4 v[80:81], v[72:75], off
	v_cvt_pk_bf16_f32 v68, v68, v69
	v_cvt_pk_bf16_f32 v69, v70, v71
	v_cvt_pk_bf16_f32 v70, v64, v65
	v_lshl_add_u64 v[64:65], v[138:139], 0, s[2:3]
	s_mov_b32 s2, 0x80000
	v_cvt_pk_bf16_f32 v71, v66, v67
	global_store_dwordx4 v[80:81], v[68:71], off offset:256
	v_cvt_pk_bf16_f32 v60, v60, v61
	v_cvt_pk_bf16_f32 v61, v62, v63
	v_cvt_pk_bf16_f32 v62, v56, v57
	v_add_co_u32_e32 v56, vcc, s2, v138
	v_cvt_pk_bf16_f32 v63, v58, v59
	s_mov_b64 s[2:3], 0x90000
	s_nop 0
	v_addc_co_u32_e32 v57, vcc, 0, v139, vcc
	global_store_dwordx4 v[56:57], v[60:63], off
	v_cvt_pk_bf16_f32 v48, v48, v49
	v_cvt_pk_bf16_f32 v49, v50, v51
	v_cvt_pk_bf16_f32 v50, v40, v41
	v_cvt_pk_bf16_f32 v51, v42, v43
	global_store_dwordx4 v[64:65], v[48:51], off offset:256
	v_cvt_pk_bf16_f32 v40, v52, v53
	v_cvt_pk_bf16_f32 v41, v54, v55
	v_cvt_pk_bf16_f32 v42, v44, v45
	v_cvt_pk_bf16_f32 v43, v46, v47
	s_mov_b64 s[78:79], 0x2000
	s_nop 0
	v_lshl_add_u64 v[48:49], v[138:139], 0, s[2:3]
	s_mov_b32 s2, 0x90000
	v_add_co_u32_e32 v44, vcc, s2, v138
	s_mov_b64 s[2:3], 0xa0000
	s_nop 0
	v_addc_co_u32_e32 v45, vcc, 0, v139, vcc
	global_store_dwordx4 v[44:45], v[40:43], off
	v_cvt_pk_bf16_f32 v32, v32, v33
	v_cvt_pk_bf16_f32 v33, v34, v35
	v_cvt_pk_bf16_f32 v34, v24, v25
	v_cvt_pk_bf16_f32 v35, v26, v27
	global_store_dwordx4 v[48:49], v[32:35], off offset:256
	v_cvt_pk_bf16_f32 v24, v36, v37
	v_cvt_pk_bf16_f32 v25, v38, v39
	v_cvt_pk_bf16_f32 v26, v28, v29
	v_cvt_pk_bf16_f32 v27, v30, v31
	s_nop 1
	v_lshl_add_u64 v[32:33], v[138:139], 0, s[2:3]
	s_mov_b32 s2, 0xa0000
	v_add_co_u32_e32 v28, vcc, s2, v138
	s_mov_b64 s[2:3], 0xb0000
	s_nop 0
	v_addc_co_u32_e32 v29, vcc, 0, v139, vcc
	global_store_dwordx4 v[28:29], v[24:27], off
	v_cvt_pk_bf16_f32 v16, v16, v17
	v_cvt_pk_bf16_f32 v17, v18, v19
	v_cvt_pk_bf16_f32 v18, v8, v9
	v_cvt_pk_bf16_f32 v19, v10, v11
	global_store_dwordx4 v[32:33], v[16:19], off offset:256
	v_cvt_pk_bf16_f32 v8, v20, v21
	v_cvt_pk_bf16_f32 v9, v22, v23
	v_cvt_pk_bf16_f32 v10, v12, v13
	v_cvt_pk_bf16_f32 v11, v14, v15
	s_nop 1
	v_lshl_add_u64 v[16:17], v[138:139], 0, s[2:3]
	s_mov_b32 s2, 0xb0000
	v_add_co_u32_e32 v12, vcc, s2, v138
	s_mov_b64 s[2:3], s[28:29]
	s_nop 0
	v_addc_co_u32_e32 v13, vcc, 0, v139, vcc
	s_and_b64 vcc, exec, s[14:15]
	global_store_dwordx4 v[12:13], v[8:11], off
	v_cvt_pk_bf16_f32 v4, v4, v5
	v_cvt_pk_bf16_f32 v5, v6, v7
	v_cvt_pk_bf16_f32 v6, v0, v1
	v_cvt_pk_bf16_f32 v7, v2, v3
	global_store_dwordx4 v[16:17], v[4:7], off offset:256
	s_cbranch_vccz .LBB0_232
	s_waitcnt vmcnt(0)
	s_cmpk_gt_u32 s40, 0xff
	s_cbranch_scc1 .LBB0_246
	s_barrier

.LBB0_249:
	v_readlane_b32 s2, v255, 10
	s_lshl_b32 s40, s2, 5
	v_readlane_b32 s2, v251, 0
	v_mov_b32_e32 v0, v224
	s_cmp_ge_i32 s2, s40
	s_nop 0
	v_readfirstlane_b32 s41, v0
	s_cbranch_scc1 .LBB0_261
	v_lshlrev_b32_e32 v4, 4, v0
	v_add_u32_e32 v2, 0x2000, v4
	s_waitcnt lgkmcnt(0)
	v_ashrrev_i32_e32 v1, 31, v2
	v_lshrrev_b32_e32 v1, 22, v1
	s_ashr_i32 s14, s41, 6
	v_add_u32_e32 v1, v2, v1
	s_ashr_i32 s15, s41, 8
	s_lshl_b32 s50, s14, 10
	v_readlane_b32 s2, v252, 1
	v_ashrrev_i32_e32 v1, 10, v1
	s_add_u32 s51, s2, s0
	v_readlane_b32 s0, v252, 2
	v_readlane_b32 s3, v255, 10
	v_mul_i32_i24_e32 v3, 0x400, v1
	s_addc_u32 s52, s0, s1
	s_lshl_b32 s53, s3, 2
	v_readlane_b32 s0, v252, 61
	v_sub_u32_e32 v2, v2, v3
	s_or_b32 s0, s53, s0
	v_readlane_b32 s1, v252, 60
	v_lshrrev_b32_e32 v3, 4, v2
	s_mul_i32 s0, s0, s1
	v_readlane_b32 s1, v252, 59
	v_bitop3_b32 v3, v3, v2, 32 bitop3:0x6c
	s_add_i32 s0, s0, s1
	v_ashrrev_i32_e32 v2, 31, v3
	s_ashr_i32 s1, s0, 31
	v_lshrrev_b32_e32 v2, 26, v2
	s_lshr_b32 s1, s1, 24
	v_add_u32_e32 v5, v3, v2
	v_lshlrev_b32_e32 v6, 3, v1
	s_add_i32 s1, s0, s1
	v_ashrrev_i32_e32 v2, 6, v5
	v_and_b32_e32 v6, -16, v6
	s_ashr_i32 s2, s1, 8
	s_and_b32 s1, s1, 0xffffff00
	v_add_u32_e32 v6, v2, v6
	s_sub_i32 s4, s0, s1
	v_and_b32_e32 v7, 3, v2
	s_mov_b32 s0, 0xfffe0
	v_lshrrev_b32_e32 v8, 2, v6
	v_lshlrev_b32_e32 v9, 1, v6
	v_and_b32_e32 v5, 0xc0, v5
	v_and_or_b32 v7, v6, s0, v7
	v_and_b32_e32 v8, 4, v8
	v_and_b32_e32 v9, 24, v9
	v_sub_u32_e32 v3, v3, v5
	v_or3_b32 v7, v7, v8, v9
	v_lshlrev_b32_e32 v8, 5, v1
	v_ashrrev_i16_sdwa v3, v226, sext(v3) dst_sel:DWORD dst_unused:UNUSED_PAD src0_sel:DWORD src1_sel:BYTE_0
	v_and_b32_e32 v8, 32, v8
	v_bfe_i32 v3, v3, 0, 16
	v_add_lshl_u32 v5, v8, v3, 1
	v_lshl_add_u32 v128, v7, 12, v5
	v_lshl_add_u32 v130, v6, 12, v5
	v_bfe_i32 v5, v0, 27, 1
	v_lshrrev_b32_e32 v5, 22, v5
	v_add_u32_e32 v5, v4, v5
	v_and_b32_e32 v5, 0xfffffc00, v5
	v_sub_u32_e32 v4, v4, v5
	v_lshrrev_b32_e32 v5, 4, v4
	v_bitop3_b32 v6, v5, v4, 32 bitop3:0x6c
	v_ashrrev_i32_e32 v5, 31, v0
	v_lshrrev_b32_e32 v5, 26, v5
	v_ashrrev_i32_e32 v4, 31, v4
	v_add_u32_e32 v5, v0, v5
	v_lshrrev_b32_e32 v4, 26, v4
	v_ashrrev_i32_e32 v5, 6, v5
	v_add_u32_e32 v4, v6, v4
	v_lshlrev_b32_e32 v7, 3, v5
	v_ashrrev_i32_e32 v4, 6, v4
	v_and_b32_e32 v7, -16, v7
	s_lshl_b32 s2, s2, 3
	v_add_u32_e32 v7, v4, v7
	s_sub_i32 s3, s3, s2
	v_and_b32_e32 v8, 3, v4
	v_lshrrev_b32_e32 v9, 2, v7
	v_lshlrev_b32_e32 v10, 1, v7
	s_min_i32 s3, s3, 8
	v_and_or_b32 v8, v7, s0, v8
	v_and_b32_e32 v9, 4, v9
	v_and_b32_e32 v10, 24, v10
	v_or3_b32 v8, v8, v9, v10
	v_mul_i32_i24_e32 v10, 64, v4
	s_sext_i32_i16 s0, s3
	v_sub_u32_e32 v6, v6, v10
	v_cvt_f32_i32_e32 v10, s0
	v_lshlrev_b32_e32 v9, 5, v5
	v_ashrrev_i16_sdwa v6, v226, sext(v6) dst_sel:DWORD dst_unused:UNUSED_PAD src0_sel:DWORD src1_sel:BYTE_0
	v_and_b32_e32 v9, 32, v9
	v_bfe_i32 v6, v6, 0, 16
	v_add_lshl_u32 v9, v9, v6, 1
	v_lshl_add_u32 v192, v8, 12, v9
	v_lshl_add_u32 v132, v7, 12, v9
	v_cvt_f32_i32_e32 v7, s4
	v_rcp_iflag_f32_e32 v8, v10
	s_xor_b32 s0, s4, s0
	s_ashr_i32 s0, s0, 30
	s_or_b32 s5, s0, 1
	v_mul_f32_e32 v8, v7, v8
	v_trunc_f32_e32 v8, v8
	v_fma_f32 v7, -v8, v10, v7
	v_cvt_i32_f32_e32 v8, v8
	v_cmp_ge_f32_e64 s[0:1], |v7|, |v10|
	s_and_b64 s[0:1], s[0:1], exec
	s_cselect_b32 s0, s5, 0
	v_readfirstlane_b32 s1, v8
	s_add_i32 s0, s1, s0
	s_mul_i32 s1, s0, s3
	s_sub_i32 s1, s4, s1
	s_sext_i32_i16 s1, s1
	s_add_i32 s38, s2, s1
	s_ashr_i32 s39, s38, 31
	s_lshl_b64 s[2:3], s[38:39], 20
	v_readlane_b32 s4, v253, 31
	v_readlane_b32 s5, v253, 32
	s_add_u32 s2, s4, s2
	s_addc_u32 s3, s5, s3
	s_bfe_i64 s[4:5], s[0:1], 0x100000
	s_lshl_b64 s[4:5], s[4:5], 20
	s_add_u32 s4, s51, s4
	s_addc_u32 s5, s52, s5
	s_add_i32 s39, s50, 0
	s_add_i32 m0, s39, 0x10000
	s_add_i32 s54, s39, 0x2000
	global_load_lds_dwordx4 v192, s[4:5]
	s_add_i32 m0, s39, 0x12000
	s_add_u32 s28, s4, 0x80000
	global_load_lds_dwordx4 v128, s[4:5]
	s_mov_b32 m0, s39
	s_addc_u32 s29, s5, 0
	global_load_lds_dwordx4 v132, s[2:3]
	s_mov_b32 m0, s54
	v_lshl_add_u64 v[8:9], s[4:5], 0, v[192:193]
	global_load_lds_dwordx4 v130, s[2:3]
	s_add_i32 m0, s39, 0x14000
	v_mov_b32_e32 v129, v193
	global_load_lds_dwordx4 v192, s[28:29]
	s_add_i32 m0, s39, 0x16000
	v_lshl_add_u64 v[10:11], s[4:5], 0, v[128:129]
	global_load_lds_dwordx4 v128, s[28:29]
	s_add_u32 s28, s2, 0x80000
	s_addc_u32 s29, s3, 0
	s_add_i32 s55, s39, 0x4000
	s_mov_b32 m0, s55
	s_add_i32 s58, s39, 0x6000
	global_load_lds_dwordx4 v132, s[28:29]
	s_mov_b32 m0, s58
	v_mov_b32_e32 v133, v193
	global_load_lds_dwordx4 v130, s[28:29]
	s_add_i32 m0, s39, 0x18000
	v_lshl_add_u64 v[8:9], v[8:9], 0, s[72:73]
	v_lshl_add_u64 v[12:13], s[2:3], 0, v[132:133]
	v_mov_b32_e32 v131, v193
	global_load_lds_dwordx4 v[8:9], off
	v_lshl_add_u64 v[8:9], v[10:11], 0, s[72:73]
	s_add_i32 m0, s39, 0x1a000
	s_add_i32 s59, s39, 0x8000
	v_lshl_add_u64 v[14:15], s[2:3], 0, v[130:131]
	global_load_lds_dwordx4 v[8:9], off
	v_lshl_add_u64 v[8:9], v[12:13], 0, s[72:73]
	s_mov_b32 m0, s59
	s_add_i32 s62, s39, 0xa000
	global_load_lds_dwordx4 v[8:9], off
	v_lshl_add_u64 v[8:9], v[14:15], 0, s[72:73]
	s_mov_b32 m0, s62
	s_add_u32 s28, s4, 0x80080
	global_load_lds_dwordx4 v[8:9], off
	s_addc_u32 s29, s5, 0
	s_add_i32 m0, s39, 0x1c000
	s_nop 0
	global_load_lds_dwordx4 v192, s[28:29]
	s_add_i32 m0, s39, 0x1e000
	s_mov_b32 s98, s15
	s_cmp_lg_u32 s15, 1
	global_load_lds_dwordx4 v128, s[28:29]
	s_cbranch_scc1 .LBB0_252
	s_barrier

.LBB0_256:
	v_add_u32_e32 v138, 0x10000, v141
	ds_read_b128 v[144:147], v138
	ds_read_b128 v[148:151], v138 offset:1024
	ds_read_b128 v[152:155], v138 offset:2048
	ds_read_b128 v[156:159], v138 offset:3072
	ds_read_b128 v[160:163], v142
	ds_read_b128 v[164:167], v142 offset:1024
	ds_read_b128 v[168:171], v142 offset:2048
	ds_read_b128 v[172:175], v142 offset:3072
	ds_read_b128 v[176:179], v142 offset:4096
	ds_read_b128 v[180:183], v142 offset:5120
	ds_read_b128 v[184:187], v142 offset:6144
	ds_read_b128 v[188:191], v142 offset:7168
	v_add_u32_e32 v138, 0x14000, v141
	ds_read_b128 v[194:197], v138
	ds_read_b128 v[198:201], v138 offset:1024
	ds_read_b128 v[202:205], v138 offset:2048
	ds_read_b128 v[206:209], v138 offset:3072
	s_add_u32 s4, s2, 0xfff80080
	s_addc_u32 s5, s3, -1
	s_add_i32 s9, 0, 0x10000
	s_cmp_eq_u32 s69, 28
	s_cselect_b32 s49, s35, s5
	s_cselect_b32 s48, s34, s4
	s_cselect_b32 s5, s37, s29
	s_cselect_b32 s4, s36, s15
	v_lshl_add_u64 v[138:139], s[2:3], 0, v[134:135]
	s_add_i32 m0, s39, 0xc000
	s_nop 0
	global_load_lds_dwordx4 v[138:139], off
	v_lshl_add_u64 v[138:139], s[2:3], 0, v[136:137]
	s_add_i32 m0, s39, 0xe000
	s_nop 0
	global_load_lds_dwordx4 v[138:139], off
	s_cmp_eq_u32 s98, 0
	s_cbranch_scc1 .Lawa256w1
	s_waitcnt vmcnt(8)
.Lawa256w1:
	s_waitcnt lgkmcnt(0)
	s_barrier
	s_setprio 1
	v_mfma_f32_16x16x32_bf16 v[124:127], v[144:147], v[160:163], v[124:127]
	v_mfma_f32_16x16x32_bf16 v[120:123], v[152:155], v[160:163], v[120:123]
	v_mfma_f32_16x16x32_bf16 v[108:111], v[144:147], v[168:171], v[108:111]
	v_mfma_f32_16x16x32_bf16 v[104:107], v[152:155], v[168:171], v[104:107]
	v_mfma_f32_16x16x32_bf16 v[92:95], v[144:147], v[176:179], v[92:95]
	v_mfma_f32_16x16x32_bf16 v[88:91], v[152:155], v[176:179], v[88:91]
	v_mfma_f32_16x16x32_bf16 v[76:79], v[144:147], v[184:187], v[76:79]
	v_mfma_f32_16x16x32_bf16 v[72:75], v[152:155], v[184:187], v[72:75]
	v_mfma_f32_16x16x32_bf16 v[124:127], v[148:151], v[164:167], v[124:127]
	v_mfma_f32_16x16x32_bf16 v[120:123], v[156:159], v[164:167], v[120:123]
	v_mfma_f32_16x16x32_bf16 v[108:111], v[148:151], v[172:175], v[108:111]
	v_mfma_f32_16x16x32_bf16 v[104:107], v[156:159], v[172:175], v[104:107]
	v_mfma_f32_16x16x32_bf16 v[92:95], v[148:151], v[180:183], v[92:95]
	v_mfma_f32_16x16x32_bf16 v[88:91], v[156:159], v[180:183], v[88:91]
	v_mfma_f32_16x16x32_bf16 v[76:79], v[148:151], v[188:191], v[76:79]
	v_mfma_f32_16x16x32_bf16 v[72:75], v[156:159], v[188:191], v[72:75]
	v_mfma_f32_16x16x32_bf16 v[116:119], v[194:197], v[160:163], v[116:119]
	v_mfma_f32_16x16x32_bf16 v[112:115], v[202:205], v[160:163], v[112:115]
	v_mfma_f32_16x16x32_bf16 v[100:103], v[194:197], v[168:171], v[100:103]
	v_mfma_f32_16x16x32_bf16 v[96:99], v[202:205], v[168:171], v[96:99]
	v_mfma_f32_16x16x32_bf16 v[84:87], v[194:197], v[176:179], v[84:87]
	v_mfma_f32_16x16x32_bf16 v[80:83], v[202:205], v[176:179], v[80:83]
	v_mfma_f32_16x16x32_bf16 v[68:71], v[194:197], v[184:187], v[68:71]
	v_mfma_f32_16x16x32_bf16 v[64:67], v[202:205], v[184:187], v[64:67]
	v_mfma_f32_16x16x32_bf16 v[116:119], v[198:201], v[164:167], v[116:119]
	v_mfma_f32_16x16x32_bf16 v[112:115], v[206:209], v[164:167], v[112:115]
	v_mfma_f32_16x16x32_bf16 v[100:103], v[198:201], v[172:175], v[100:103]
	v_mfma_f32_16x16x32_bf16 v[96:99], v[206:209], v[172:175], v[96:99]
	v_mfma_f32_16x16x32_bf16 v[84:87], v[198:201], v[180:183], v[84:87]
	v_mfma_f32_16x16x32_bf16 v[80:83], v[206:209], v[180:183], v[80:83]
	v_mfma_f32_16x16x32_bf16 v[68:71], v[198:201], v[188:191], v[68:71]
	v_mfma_f32_16x16x32_bf16 v[64:67], v[206:209], v[188:191], v[64:67]
	s_setprio 0
	s_cmp_lg_u32 s98, 0
	s_cbranch_scc1 .Lawa256w2
	s_waitcnt vmcnt(8)
.Lawa256w2:
	s_barrier
	ds_read_b128 v[160:163], v142 offset:16384
	ds_read_b128 v[164:167], v142 offset:17408
	ds_read_b128 v[168:171], v142 offset:18432
	ds_read_b128 v[172:175], v142 offset:19456
	ds_read_b128 v[176:179], v142 offset:20480
	ds_read_b128 v[180:183], v142 offset:21504
	ds_read_b128 v[184:187], v142 offset:22528
	ds_read_b128 v[188:191], v142 offset:23552
	s_add_i32 s71, 0, 0x14000
	s_add_i32 s9, s9, s50
	v_lshl_add_u64 v[138:139], s[4:5], 0, v[192:193]
	s_mov_b32 m0, s9
	v_lshl_add_u64 v[210:211], s[4:5], 0, v[128:129]
	global_load_lds_dwordx4 v[138:139], off
	s_add_i32 m0, s9, 0x2000
	s_nop 0
	global_load_lds_dwordx4 v[210:211], off
	s_mov_b32 m0, s39
	v_lshl_add_u64 v[212:213], s[48:49], 0, v[132:133]
	global_load_lds_dwordx4 v[212:213], off
	v_lshl_add_u64 v[214:215], s[48:49], 0, v[130:131]
	s_mov_b32 m0, s54
	s_nop 0
	global_load_lds_dwordx4 v[214:215], off
	s_add_u32 s46, s4, 0x80000
	s_addc_u32 s47, s5, 0
	s_add_i32 s9, s71, s50
	v_lshl_add_u64 v[218:219], s[46:47], 0, v[192:193]
	s_mov_b32 m0, s9
	s_nop 0
	global_load_lds_dwordx4 v[218:219], off
	v_lshl_add_u64 v[220:221], s[46:47], 0, v[128:129]
	s_add_i32 m0, s9, 0x2000
	s_nop 0
	global_load_lds_dwordx4 v[220:221], off
	s_cmp_eq_u32 s98, 0
	s_cbranch_scc1 .Lawa256w3
	s_waitcnt vmcnt(8)
.Lawa256w3:
	s_waitcnt lgkmcnt(0)
	s_barrier
	s_setprio 1
	v_mfma_f32_16x16x32_bf16 v[60:63], v[144:147], v[160:163], v[60:63]
	v_mfma_f32_16x16x32_bf16 v[56:59], v[152:155], v[160:163], v[56:59]
	v_mfma_f32_16x16x32_bf16 v[44:47], v[144:147], v[168:171], v[44:47]
	v_mfma_f32_16x16x32_bf16 v[40:43], v[152:155], v[168:171], v[40:43]
	v_mfma_f32_16x16x32_bf16 v[28:31], v[144:147], v[176:179], v[28:31]
	v_mfma_f32_16x16x32_bf16 v[24:27], v[152:155], v[176:179], v[24:27]
	v_mfma_f32_16x16x32_bf16 v[12:15], v[144:147], v[184:187], v[12:15]
	v_mfma_f32_16x16x32_bf16 v[8:11], v[152:155], v[184:187], v[8:11]
	v_mfma_f32_16x16x32_bf16 v[60:63], v[148:151], v[164:167], v[60:63]
	v_mfma_f32_16x16x32_bf16 v[56:59], v[156:159], v[164:167], v[56:59]
	v_mfma_f32_16x16x32_bf16 v[44:47], v[148:151], v[172:175], v[44:47]
	v_mfma_f32_16x16x32_bf16 v[40:43], v[156:159], v[172:175], v[40:43]
	v_mfma_f32_16x16x32_bf16 v[28:31], v[148:151], v[180:183], v[28:31]
	v_mfma_f32_16x16x32_bf16 v[24:27], v[156:159], v[180:183], v[24:27]
	v_mfma_f32_16x16x32_bf16 v[12:15], v[148:151], v[188:191], v[12:15]
	v_mfma_f32_16x16x32_bf16 v[8:11], v[156:159], v[188:191], v[8:11]
	v_mfma_f32_16x16x32_bf16 v[52:55], v[194:197], v[160:163], v[52:55]
	v_mfma_f32_16x16x32_bf16 v[48:51], v[202:205], v[160:163], v[48:51]
	v_mfma_f32_16x16x32_bf16 v[36:39], v[194:197], v[168:171], v[36:39]
	v_mfma_f32_16x16x32_bf16 v[32:35], v[202:205], v[168:171], v[32:35]
	v_mfma_f32_16x16x32_bf16 v[20:23], v[194:197], v[176:179], v[20:23]
	v_mfma_f32_16x16x32_bf16 v[16:19], v[202:205], v[176:179], v[16:19]
	v_mfma_f32_16x16x32_bf16 v[4:7], v[194:197], v[184:187], v[4:7]
	v_mfma_f32_16x16x32_bf16 v[0:3], v[202:205], v[184:187], v[0:3]
	v_mfma_f32_16x16x32_bf16 v[52:55], v[198:201], v[164:167], v[52:55]
	v_mfma_f32_16x16x32_bf16 v[48:51], v[206:209], v[164:167], v[48:51]
	v_mfma_f32_16x16x32_bf16 v[36:39], v[198:201], v[172:175], v[36:39]
	v_mfma_f32_16x16x32_bf16 v[32:35], v[206:209], v[172:175], v[32:35]
	v_mfma_f32_16x16x32_bf16 v[20:23], v[198:201], v[180:183], v[20:23]
	v_mfma_f32_16x16x32_bf16 v[16:19], v[206:209], v[180:183], v[16:19]
	v_mfma_f32_16x16x32_bf16 v[4:7], v[198:201], v[188:191], v[4:7]
	v_mfma_f32_16x16x32_bf16 v[0:3], v[206:209], v[188:191], v[0:3]
	s_setprio 0
	s_cmp_lg_u32 s98, 0
	s_cbranch_scc1 .Lawa256w4
	s_waitcnt vmcnt(8)
.Lawa256w4:
	s_barrier
	v_add_u32_e32 v143, 0x18000, v141
	ds_read_b128 v[144:147], v143
	ds_read_b128 v[148:151], v143 offset:1024
	ds_read_b128 v[152:155], v143 offset:2048
	ds_read_b128 v[156:159], v143 offset:3072
	ds_read_b128 v[160:163], v142 offset:32768
	ds_read_b128 v[164:167], v142 offset:33792
	ds_read_b128 v[168:171], v142 offset:34816
	ds_read_b128 v[172:175], v142 offset:35840
	ds_read_b128 v[176:179], v142 offset:36864
	ds_read_b128 v[180:183], v142 offset:37888
	ds_read_b128 v[184:187], v142 offset:38912
	ds_read_b128 v[188:191], v142 offset:39936
	v_add_u32_e32 v143, 0x1c000, v141
	ds_read_b128 v[194:197], v143
	ds_read_b128 v[198:201], v143 offset:1024
	ds_read_b128 v[202:205], v143 offset:2048
	ds_read_b128 v[206:209], v143 offset:3072
	s_add_i32 s9, 0, 0x18000
	s_add_u32 s46, s48, 0x80000
	s_addc_u32 s47, s49, 0
	s_mov_b32 m0, s55
	v_lshl_add_u64 v[218:219], s[46:47], 0, v[132:133]
	global_load_lds_dwordx4 v[218:219], off
	v_lshl_add_u64 v[220:221], s[46:47], 0, v[130:131]
	s_mov_b32 m0, s58
	s_nop 0
	global_load_lds_dwordx4 v[220:221], off
	s_cmp_eq_u32 s98, 0
	s_cbranch_scc1 .Lawa256w5
	s_waitcnt vmcnt(8)

.Lawa256w6:
	s_barrier
	ds_read_b128 v[160:163], v142 offset:49152
	ds_read_b128 v[164:167], v142 offset:50176
	ds_read_b128 v[168:171], v142 offset:51200
	ds_read_b128 v[172:175], v142 offset:52224
	ds_read_b128 v[176:179], v142 offset:53248
	ds_read_b128 v[180:183], v142 offset:54272
	ds_read_b128 v[184:187], v142 offset:55296
	ds_read_b128 v[188:191], v142 offset:56320
	s_add_i32 s46, 0, 0x1c000
	s_add_i32 s9, s9, s50
	v_lshl_add_u64 v[138:139], v[138:139], 0, s[72:73]
	s_mov_b32 m0, s9
	s_nop 0
	global_load_lds_dwordx4 v[138:139], off
	v_lshl_add_u64 v[138:139], v[210:211], 0, s[72:73]
	s_add_i32 m0, s9, 0x2000
	s_nop 0
	global_load_lds_dwordx4 v[138:139], off
	s_mov_b32 m0, s59
	v_lshl_add_u64 v[138:139], v[212:213], 0, s[72:73]
	global_load_lds_dwordx4 v[138:139], off
	v_lshl_add_u64 v[138:139], v[214:215], 0, s[72:73]
	s_mov_b32 m0, s62
	s_nop 0
	global_load_lds_dwordx4 v[138:139], off
	s_add_u32 s4, s4, 0x80080
	s_addc_u32 s5, s5, 0
	s_add_i32 s9, s46, s50
	v_lshl_add_u64 v[138:139], s[4:5], 0, v[192:193]
	s_mov_b32 m0, s9
	s_nop 0
	global_load_lds_dwordx4 v[138:139], off
	v_lshl_add_u64 v[138:139], s[4:5], 0, v[128:129]
	s_add_i32 m0, s9, 0x2000
	s_nop 0
	global_load_lds_dwordx4 v[138:139], off
	s_cmp_eq_u32 s98, 0
	s_cbranch_scc1 .Lawa256w7
	s_waitcnt vmcnt(8)

.Lawa256w8:
	s_add_i32 s69, s69, 2
	s_add_u32 s2, s2, 0x100
	s_addc_u32 s3, s3, 0
	s_add_u32 s15, s15, 0x100
	s_addc_u32 s29, s29, 0
	s_cmp_gt_u32 s69, 29
	s_barrier
	s_cbranch_scc0 .LBB0_256
	s_lshl_b32 s2, s38, 8
	v_mov_b32 v138, v140
	s_add_i32 s2, s2, s63
	v_and_or_b32 v144, v138, 15, s2
	s_lshl_b32 s2, s67, 8
	v_ashrrev_i32_e32 v138, 1, v138
	v_max_f32_e32 v120, v120, v120
	s_or_b32 s2, s2, s64
	v_and_b32_e32 v138, -8, v138
	v_max_f32_e32 v120, 0, v120
	v_max_f32_e32 v121, v121, v121
	v_max_f32_e32 v122, v122, v122
	v_add_u32_e32 v138, s2, v138
	v_ashrrev_i32_e32 v145, 31, v144
	v_readlane_b32 s2, v252, 63
	v_mul_f32_e32 v143, v120, v120
	v_max_f32_e32 v120, v125, v125
	v_max_f32_e32 v121, 0, v121
	v_max_f32_e32 v122, 0, v122
	v_ashrrev_i32_e32 v139, 31, v138
	v_lshlrev_b64 v[146:147], 14, v[144:145]
	v_readlane_b32 s3, v253, 0
	v_max_f32_e32 v124, v124, v124
	v_max_f32_e32 v120, 0, v120
	v_mul_f32_e32 v125, v121, v121
	v_max_f32_e32 v121, v126, v126
	v_mul_f32_e32 v126, v122, v122
	v_max_f32_e32 v122, v127, v127
	v_max_f32_e32 v123, v123, v123
	v_lshl_add_u64 v[146:147], s[2:3], 0, v[146:147]
	v_lshlrev_b64 v[148:149], 1, v[138:139]
	v_max_f32_e32 v124, 0, v124
	v_mul_f32_e32 v120, v120, v120
	v_max_f32_e32 v121, 0, v121
	v_max_f32_e32 v122, 0, v122
	v_max_f32_e32 v123, 0, v123
	v_max_f32_e32 v112, v112, v112
	v_lshl_add_u64 v[138:139], v[146:147], 0, v[148:149]
	v_mul_f32_e32 v124, v124, v124
	v_mul_f32_e32 v121, v121, v121
	v_mul_f32_e32 v122, v122, v122
	v_mul_f32_e32 v123, v123, v123
	v_cvt_pk_bf16_f32 v120, v124, v120
	v_max_f32_e32 v112, 0, v112
	v_max_f32_e32 v113, v113, v113
	v_max_f32_e32 v114, v114, v114
	v_cvt_pk_bf16_f32 v121, v121, v122
	v_cvt_pk_bf16_f32 v122, v143, v125
	v_cvt_pk_bf16_f32 v123, v126, v123
	global_store_dwordx4 v[138:139], v[120:123], off
	v_max_f32_e32 v113, 0, v113
	v_max_f32_e32 v114, 0, v114
	v_mul_f32_e32 v120, v112, v112
	v_max_f32_e32 v112, v117, v117
	v_max_f32_e32 v116, v116, v116
	v_max_f32_e32 v112, 0, v112
	v_mul_f32_e32 v117, v113, v113
	v_max_f32_e32 v113, v118, v118
	v_mul_f32_e32 v118, v114, v114
	v_max_f32_e32 v114, v119, v119
	v_max_f32_e32 v115, v115, v115
	v_max_f32_e32 v116, 0, v116
	v_mul_f32_e32 v112, v112, v112
	v_max_f32_e32 v113, 0, v113
	v_max_f32_e32 v114, 0, v114
	v_max_f32_e32 v115, 0, v115
	v_mul_f32_e32 v116, v116, v116
	v_mul_f32_e32 v113, v113, v113
	v_mul_f32_e32 v114, v114, v114
	v_mul_f32_e32 v115, v115, v115
	v_cvt_pk_bf16_f32 v112, v116, v112
	v_max_f32_e32 v104, v104, v104
	v_cvt_pk_bf16_f32 v113, v113, v114
	v_cvt_pk_bf16_f32 v114, v120, v117
	v_cvt_pk_bf16_f32 v115, v118, v115
	global_store_dwordx4 v[138:139], v[112:115], off offset:256
	v_max_f32_e32 v104, 0, v104
	v_max_f32_e32 v105, v105, v105
	v_or_b32_e32 v112, 16, v144
	v_max_f32_e32 v106, v106, v106
	v_ashrrev_i32_e32 v113, 31, v112
	v_mul_f32_e32 v114, v104, v104
	v_max_f32_e32 v104, v109, v109
	v_max_f32_e32 v105, 0, v105
	v_max_f32_e32 v106, 0, v106
	v_lshlrev_b64 v[112:113], 14, v[112:113]
	v_max_f32_e32 v108, v108, v108
	v_max_f32_e32 v104, 0, v104
	v_mul_f32_e32 v109, v105, v105
	v_max_f32_e32 v105, v110, v110
	v_mul_f32_e32 v110, v106, v106
	v_max_f32_e32 v106, v111, v111
	v_max_f32_e32 v107, v107, v107
	v_lshl_add_u64 v[112:113], s[2:3], 0, v[112:113]
	v_max_f32_e32 v108, 0, v108
	v_mul_f32_e32 v104, v104, v104
	v_max_f32_e32 v105, 0, v105
	v_max_f32_e32 v106, 0, v106
	v_max_f32_e32 v107, 0, v107
	v_max_f32_e32 v96, v96, v96
	v_lshl_add_u64 v[112:113], v[112:113], 0, v[148:149]
	v_mul_f32_e32 v108, v108, v108
	v_mul_f32_e32 v105, v105, v105
	v_mul_f32_e32 v106, v106, v106
	v_mul_f32_e32 v107, v107, v107
	v_cvt_pk_bf16_f32 v104, v108, v104
	v_max_f32_e32 v96, 0, v96
	v_max_f32_e32 v97, v97, v97
	v_max_f32_e32 v98, v98, v98
	v_cvt_pk_bf16_f32 v105, v105, v106
	v_cvt_pk_bf16_f32 v106, v114, v109
	v_cvt_pk_bf16_f32 v107, v110, v107
	global_store_dwordx4 v[112:113], v[104:107], off
	v_max_f32_e32 v97, 0, v97
	v_max_f32_e32 v98, 0, v98
	v_mul_f32_e32 v104, v96, v96
	v_max_f32_e32 v96, v101, v101
	v_max_f32_e32 v100, v100, v100
	v_max_f32_e32 v96, 0, v96
	v_mul_f32_e32 v101, v97, v97
	v_max_f32_e32 v97, v102, v102
	v_mul_f32_e32 v102, v98, v98
	v_max_f32_e32 v98, v103, v103
	v_max_f32_e32 v99, v99, v99
	v_max_f32_e32 v100, 0, v100
	v_mul_f32_e32 v96, v96, v96
	v_max_f32_e32 v97, 0, v97
	v_max_f32_e32 v98, 0, v98
	v_max_f32_e32 v99, 0, v99
	v_mul_f32_e32 v100, v100, v100
	v_mul_f32_e32 v97, v97, v97
	v_mul_f32_e32 v98, v98, v98
	v_mul_f32_e32 v99, v99, v99
	v_cvt_pk_bf16_f32 v96, v100, v96
	v_max_f32_e32 v88, v88, v88
	v_cvt_pk_bf16_f32 v97, v97, v98
	v_cvt_pk_bf16_f32 v98, v104, v101
	v_cvt_pk_bf16_f32 v99, v102, v99
	global_store_dwordx4 v[112:113], v[96:99], off offset:256
	v_max_f32_e32 v88, 0, v88
	v_max_f32_e32 v89, v89, v89
	v_or_b32_e32 v96, 32, v144
	v_max_f32_e32 v90, v90, v90
	v_ashrrev_i32_e32 v97, 31, v96
	v_mul_f32_e32 v98, v88, v88
	v_max_f32_e32 v88, v93, v93
	v_max_f32_e32 v89, 0, v89
	v_max_f32_e32 v90, 0, v90
	v_lshlrev_b64 v[96:97], 14, v[96:97]
	v_max_f32_e32 v92, v92, v92
	v_max_f32_e32 v88, 0, v88
	v_mul_f32_e32 v93, v89, v89
	v_max_f32_e32 v89, v94, v94
	v_mul_f32_e32 v94, v90, v90
	v_max_f32_e32 v90, v95, v95
	v_max_f32_e32 v91, v91, v91
	v_lshl_add_u64 v[96:97], s[2:3], 0, v[96:97]
	v_max_f32_e32 v92, 0, v92
	v_mul_f32_e32 v88, v88, v88
	v_max_f32_e32 v89, 0, v89
	v_max_f32_e32 v90, 0, v90
	v_max_f32_e32 v91, 0, v91
	v_max_f32_e32 v80, v80, v80
	v_lshl_add_u64 v[96:97], v[96:97], 0, v[148:149]
	v_mul_f32_e32 v92, v92, v92
	v_mul_f32_e32 v89, v89, v89
	v_mul_f32_e32 v90, v90, v90
	v_mul_f32_e32 v91, v91, v91
	v_cvt_pk_bf16_f32 v88, v92, v88
	v_max_f32_e32 v80, 0, v80
	v_max_f32_e32 v81, v81, v81
	v_max_f32_e32 v82, v82, v82
	v_cvt_pk_bf16_f32 v89, v89, v90
	v_cvt_pk_bf16_f32 v90, v98, v93
	v_cvt_pk_bf16_f32 v91, v94, v91
	global_store_dwordx4 v[96:97], v[88:91], off
	v_max_f32_e32 v81, 0, v81
	v_max_f32_e32 v82, 0, v82
	v_mul_f32_e32 v88, v80, v80
	v_max_f32_e32 v80, v85, v85
	v_max_f32_e32 v84, v84, v84
	v_max_f32_e32 v80, 0, v80
	v_mul_f32_e32 v85, v81, v81
	v_max_f32_e32 v81, v86, v86
	v_mul_f32_e32 v86, v82, v82
	v_max_f32_e32 v82, v87, v87
	v_max_f32_e32 v83, v83, v83
	v_max_f32_e32 v84, 0, v84
	v_mul_f32_e32 v80, v80, v80
	v_max_f32_e32 v81, 0, v81
	v_max_f32_e32 v82, 0, v82
	v_max_f32_e32 v83, 0, v83
	v_mul_f32_e32 v84, v84, v84
	v_mul_f32_e32 v81, v81, v81
	v_mul_f32_e32 v82, v82, v82
	v_mul_f32_e32 v83, v83, v83
	v_cvt_pk_bf16_f32 v80, v84, v80
	v_max_f32_e32 v72, v72, v72
	v_cvt_pk_bf16_f32 v81, v81, v82
	v_cvt_pk_bf16_f32 v82, v88, v85
	v_cvt_pk_bf16_f32 v83, v86, v83
	global_store_dwordx4 v[96:97], v[80:83], off offset:256
	v_max_f32_e32 v72, 0, v72
	v_max_f32_e32 v73, v73, v73
	v_or_b32_e32 v80, 48, v144
	v_max_f32_e32 v74, v74, v74
	v_ashrrev_i32_e32 v81, 31, v80
	v_mul_f32_e32 v82, v72, v72
	v_max_f32_e32 v72, v77, v77
	v_max_f32_e32 v73, 0, v73
	v_max_f32_e32 v74, 0, v74
	v_lshlrev_b64 v[80:81], 14, v[80:81]
	v_max_f32_e32 v76, v76, v76
	v_max_f32_e32 v72, 0, v72
	v_mul_f32_e32 v77, v73, v73
	v_max_f32_e32 v73, v78, v78
	v_mul_f32_e32 v78, v74, v74
	v_max_f32_e32 v74, v79, v79
	v_max_f32_e32 v75, v75, v75
	v_lshl_add_u64 v[80:81], s[2:3], 0, v[80:81]
	v_max_f32_e32 v76, 0, v76
	v_mul_f32_e32 v72, v72, v72
	v_max_f32_e32 v73, 0, v73
	v_max_f32_e32 v74, 0, v74
	v_max_f32_e32 v75, 0, v75
	v_max_f32_e32 v64, v64, v64
	v_max_f32_e32 v65, v65, v65
	v_max_f32_e32 v66, v66, v66
	v_lshl_add_u64 v[80:81], v[80:81], 0, v[148:149]
	v_mul_f32_e32 v76, v76, v76
	v_mul_f32_e32 v73, v73, v73
	v_mul_f32_e32 v74, v74, v74
	v_mul_f32_e32 v75, v75, v75
	v_cvt_pk_bf16_f32 v72, v76, v72
	v_max_f32_e32 v64, 0, v64
	v_max_f32_e32 v65, 0, v65
	v_max_f32_e32 v66, 0, v66
	v_cvt_pk_bf16_f32 v73, v73, v74
	v_cvt_pk_bf16_f32 v74, v82, v77
	v_cvt_pk_bf16_f32 v75, v78, v75
	global_store_dwordx4 v[80:81], v[72:75], off
	v_max_f32_e32 v68, v68, v68
	v_max_f32_e32 v67, v67, v67
	v_mul_f32_e32 v72, v64, v64
	v_max_f32_e32 v64, v69, v69
	v_mul_f32_e32 v69, v65, v65
	v_max_f32_e32 v65, v70, v70
	v_mul_f32_e32 v70, v66, v66
	v_max_f32_e32 v66, v71, v71
	v_max_f32_e32 v64, 0, v64
	v_max_f32_e32 v65, 0, v65
	v_max_f32_e32 v66, 0, v66
	v_max_f32_e32 v68, 0, v68
	v_mul_f32_e32 v64, v64, v64
	v_mul_f32_e32 v65, v65, v65
	v_max_f32_e32 v67, 0, v67
	v_mul_f32_e32 v66, v66, v66
	v_max_f32_e32 v56, v56, v56
	v_mul_f32_e32 v68, v68, v68
	v_mul_f32_e32 v67, v67, v67
	v_cvt_pk_bf16_f32 v64, v68, v64
	v_cvt_pk_bf16_f32 v65, v65, v66
	v_cvt_pk_bf16_f32 v66, v72, v69
	v_max_f32_e32 v56, 0, v56
	v_max_f32_e32 v57, v57, v57
	v_max_f32_e32 v58, v58, v58
	v_cvt_pk_bf16_f32 v67, v70, v67
	global_store_dwordx4 v[80:81], v[64:67], off offset:256
	v_max_f32_e32 v60, v60, v60
	v_max_f32_e32 v57, 0, v57
	v_mul_f32_e32 v66, v56, v56
	v_max_f32_e32 v56, v61, v61
	v_max_f32_e32 v58, 0, v58
	s_mov_b64 s[2:3], 0x200000
	v_max_f32_e32 v60, 0, v60
	v_max_f32_e32 v56, 0, v56
	v_mul_f32_e32 v61, v57, v57
	v_max_f32_e32 v57, v62, v62
	v_mul_f32_e32 v62, v58, v58
	v_max_f32_e32 v58, v63, v63
	v_lshl_add_u64 v[64:65], v[138:139], 0, s[2:3]
	v_mul_f32_e32 v60, v60, v60
	v_mul_f32_e32 v56, v56, v56
	v_max_f32_e32 v57, 0, v57
	v_max_f32_e32 v58, 0, v58
	v_max_f32_e32 v59, v59, v59
	s_mov_b32 s2, 0x200000
	v_mul_f32_e32 v57, v57, v57
	v_max_f32_e32 v59, 0, v59
	v_mul_f32_e32 v58, v58, v58
	v_cvt_pk_bf16_f32 v56, v60, v56
	v_add_co_u32_e32 v60, vcc, s2, v138
	v_max_f32_e32 v48, v48, v48
	v_max_f32_e32 v49, v49, v49
	v_max_f32_e32 v50, v50, v50
	v_mul_f32_e32 v59, v59, v59
	v_cvt_pk_bf16_f32 v57, v57, v58
	v_cvt_pk_bf16_f32 v58, v66, v61
	v_addc_co_u32_e32 v61, vcc, 0, v139, vcc
	v_max_f32_e32 v48, 0, v48
	v_max_f32_e32 v49, 0, v49
	v_max_f32_e32 v50, 0, v50
	v_cvt_pk_bf16_f32 v59, v62, v59
	global_store_dwordx4 v[60:61], v[56:59], off
	v_max_f32_e32 v52, v52, v52
	v_max_f32_e32 v51, v51, v51
	v_mul_f32_e32 v56, v48, v48
	v_max_f32_e32 v48, v53, v53
	v_mul_f32_e32 v53, v49, v49
	v_max_f32_e32 v49, v54, v54
	v_mul_f32_e32 v54, v50, v50
	v_max_f32_e32 v50, v55, v55
	v_max_f32_e32 v48, 0, v48
	v_max_f32_e32 v49, 0, v49
	v_max_f32_e32 v50, 0, v50
	v_max_f32_e32 v52, 0, v52
	v_mul_f32_e32 v48, v48, v48
	v_mul_f32_e32 v49, v49, v49
	v_max_f32_e32 v51, 0, v51
	v_mul_f32_e32 v50, v50, v50
	v_max_f32_e32 v40, v40, v40
	v_mul_f32_e32 v52, v52, v52
	v_mul_f32_e32 v51, v51, v51
	v_cvt_pk_bf16_f32 v48, v52, v48
	v_cvt_pk_bf16_f32 v49, v49, v50
	v_cvt_pk_bf16_f32 v50, v56, v53
	v_max_f32_e32 v40, 0, v40
	v_max_f32_e32 v41, v41, v41
	v_max_f32_e32 v42, v42, v42
	v_cvt_pk_bf16_f32 v51, v54, v51
	global_store_dwordx4 v[64:65], v[48:51], off offset:256
	v_max_f32_e32 v44, v44, v44
	v_max_f32_e32 v41, 0, v41
	v_mul_f32_e32 v50, v40, v40
	v_max_f32_e32 v40, v45, v45
	v_max_f32_e32 v42, 0, v42
	s_mov_b64 s[2:3], 0x240000
	v_max_f32_e32 v44, 0, v44
	v_max_f32_e32 v40, 0, v40
	v_mul_f32_e32 v45, v41, v41
	v_max_f32_e32 v41, v46, v46
	v_mul_f32_e32 v46, v42, v42
	v_max_f32_e32 v42, v47, v47
	v_lshl_add_u64 v[48:49], v[138:139], 0, s[2:3]
	v_mul_f32_e32 v44, v44, v44
	v_mul_f32_e32 v40, v40, v40
	v_max_f32_e32 v41, 0, v41
	v_max_f32_e32 v42, 0, v42
	v_max_f32_e32 v43, v43, v43
	s_mov_b32 s2, 0x240000
	v_mul_f32_e32 v41, v41, v41
	v_max_f32_e32 v43, 0, v43
	v_mul_f32_e32 v42, v42, v42
	v_cvt_pk_bf16_f32 v40, v44, v40
	v_add_co_u32_e32 v44, vcc, s2, v138
	v_max_f32_e32 v32, v32, v32
	v_max_f32_e32 v33, v33, v33
	v_max_f32_e32 v34, v34, v34
	v_mul_f32_e32 v43, v43, v43
	v_cvt_pk_bf16_f32 v41, v41, v42
	v_cvt_pk_bf16_f32 v42, v50, v45
	v_addc_co_u32_e32 v45, vcc, 0, v139, vcc
	v_max_f32_e32 v32, 0, v32
	v_max_f32_e32 v33, 0, v33
	v_max_f32_e32 v34, 0, v34
	v_cvt_pk_bf16_f32 v43, v46, v43
	global_store_dwordx4 v[44:45], v[40:43], off
	v_max_f32_e32 v36, v36, v36
	v_max_f32_e32 v35, v35, v35
	v_mul_f32_e32 v40, v32, v32
	v_max_f32_e32 v32, v37, v37
	v_mul_f32_e32 v37, v33, v33
	v_max_f32_e32 v33, v38, v38
	v_mul_f32_e32 v38, v34, v34
	v_max_f32_e32 v34, v39, v39
	v_max_f32_e32 v32, 0, v32
	v_max_f32_e32 v33, 0, v33
	v_max_f32_e32 v34, 0, v34
	v_max_f32_e32 v36, 0, v36
	v_mul_f32_e32 v32, v32, v32
	v_mul_f32_e32 v33, v33, v33
	v_max_f32_e32 v35, 0, v35
	v_mul_f32_e32 v34, v34, v34
	v_max_f32_e32 v24, v24, v24
	v_mul_f32_e32 v36, v36, v36
	v_mul_f32_e32 v35, v35, v35
	v_cvt_pk_bf16_f32 v32, v36, v32
	v_cvt_pk_bf16_f32 v33, v33, v34
	v_cvt_pk_bf16_f32 v34, v40, v37
	v_max_f32_e32 v24, 0, v24
	v_max_f32_e32 v25, v25, v25
	v_max_f32_e32 v26, v26, v26
	v_cvt_pk_bf16_f32 v35, v38, v35
	global_store_dwordx4 v[48:49], v[32:35], off offset:256
	v_max_f32_e32 v28, v28, v28
	v_max_f32_e32 v25, 0, v25
	v_mul_f32_e32 v34, v24, v24
	v_max_f32_e32 v24, v29, v29
	v_max_f32_e32 v26, 0, v26
	s_mov_b64 s[2:3], 0x280000
	v_max_f32_e32 v28, 0, v28
	v_max_f32_e32 v24, 0, v24
	v_mul_f32_e32 v29, v25, v25
	v_max_f32_e32 v25, v30, v30
	v_mul_f32_e32 v30, v26, v26
	v_max_f32_e32 v26, v31, v31
	v_lshl_add_u64 v[32:33], v[138:139], 0, s[2:3]
	v_mul_f32_e32 v28, v28, v28
	v_mul_f32_e32 v24, v24, v24
	v_max_f32_e32 v25, 0, v25
	v_max_f32_e32 v26, 0, v26
	v_max_f32_e32 v27, v27, v27
	s_mov_b32 s2, 0x280000
	v_mul_f32_e32 v25, v25, v25
	v_max_f32_e32 v27, 0, v27
	v_mul_f32_e32 v26, v26, v26
	v_cvt_pk_bf16_f32 v24, v28, v24
	v_add_co_u32_e32 v28, vcc, s2, v138
	v_max_f32_e32 v16, v16, v16
	v_max_f32_e32 v17, v17, v17
	v_max_f32_e32 v18, v18, v18
	v_mul_f32_e32 v27, v27, v27
	v_cvt_pk_bf16_f32 v25, v25, v26
	v_cvt_pk_bf16_f32 v26, v34, v29
	v_addc_co_u32_e32 v29, vcc, 0, v139, vcc
	v_max_f32_e32 v16, 0, v16
	v_max_f32_e32 v17, 0, v17
	v_max_f32_e32 v18, 0, v18
	v_cvt_pk_bf16_f32 v27, v30, v27
	global_store_dwordx4 v[28:29], v[24:27], off
	v_max_f32_e32 v20, v20, v20
	v_max_f32_e32 v19, v19, v19
	v_mul_f32_e32 v24, v16, v16
	v_max_f32_e32 v16, v21, v21
	v_mul_f32_e32 v21, v17, v17
	v_max_f32_e32 v17, v22, v22
	v_mul_f32_e32 v22, v18, v18
	v_max_f32_e32 v18, v23, v23
	v_max_f32_e32 v16, 0, v16
	v_max_f32_e32 v17, 0, v17
	v_max_f32_e32 v18, 0, v18
	v_max_f32_e32 v20, 0, v20
	v_mul_f32_e32 v16, v16, v16
	v_mul_f32_e32 v17, v17, v17
	v_max_f32_e32 v19, 0, v19
	v_mul_f32_e32 v18, v18, v18
	v_max_f32_e32 v8, v8, v8
	v_mul_f32_e32 v20, v20, v20
	v_mul_f32_e32 v19, v19, v19
	v_cvt_pk_bf16_f32 v16, v20, v16
	v_cvt_pk_bf16_f32 v17, v17, v18
	v_cvt_pk_bf16_f32 v18, v24, v21
	v_max_f32_e32 v8, 0, v8
	v_max_f32_e32 v9, v9, v9
	v_max_f32_e32 v10, v10, v10
	v_cvt_pk_bf16_f32 v19, v22, v19
	global_store_dwordx4 v[32:33], v[16:19], off offset:256
	v_max_f32_e32 v12, v12, v12
	v_max_f32_e32 v9, 0, v9
	v_mul_f32_e32 v18, v8, v8
	v_max_f32_e32 v8, v13, v13
	v_max_f32_e32 v10, 0, v10
	s_mov_b64 s[2:3], 0x2c0000
	v_max_f32_e32 v12, 0, v12
	v_max_f32_e32 v8, 0, v8
	v_mul_f32_e32 v13, v9, v9
	v_max_f32_e32 v9, v14, v14
	v_mul_f32_e32 v14, v10, v10
	v_max_f32_e32 v10, v15, v15
	v_lshl_add_u64 v[16:17], v[138:139], 0, s[2:3]
	v_mul_f32_e32 v12, v12, v12
	v_mul_f32_e32 v8, v8, v8
	v_max_f32_e32 v9, 0, v9
	v_max_f32_e32 v10, 0, v10
	v_max_f32_e32 v11, v11, v11
	s_mov_b32 s2, 0x2c0000
	v_mul_f32_e32 v9, v9, v9
	v_max_f32_e32 v11, 0, v11
	v_mul_f32_e32 v10, v10, v10
	v_cvt_pk_bf16_f32 v8, v12, v8
	v_add_co_u32_e32 v12, vcc, s2, v138
	v_max_f32_e32 v0, v0, v0
	v_max_f32_e32 v1, v1, v1
	v_max_f32_e32 v2, v2, v2
	v_mul_f32_e32 v11, v11, v11
	v_cvt_pk_bf16_f32 v9, v9, v10
	v_cvt_pk_bf16_f32 v10, v18, v13
	v_addc_co_u32_e32 v13, vcc, 0, v139, vcc
	v_max_f32_e32 v0, 0, v0
	v_max_f32_e32 v1, 0, v1
	v_max_f32_e32 v2, 0, v2
	v_cvt_pk_bf16_f32 v11, v14, v11
	global_store_dwordx4 v[12:13], v[8:11], off
	v_max_f32_e32 v3, v3, v3
	v_max_f32_e32 v4, v4, v4
	v_mul_f32_e32 v8, v0, v0
	v_max_f32_e32 v0, v5, v5
	v_mul_f32_e32 v5, v1, v1
	v_max_f32_e32 v1, v6, v6
	v_mul_f32_e32 v6, v2, v2
	v_max_f32_e32 v2, v7, v7
	v_max_f32_e32 v0, 0, v0
	v_max_f32_e32 v1, 0, v1
	v_max_f32_e32 v2, 0, v2
	v_max_f32_e32 v3, 0, v3
	v_max_f32_e32 v4, 0, v4
	v_mul_f32_e32 v0, v0, v0
	v_mul_f32_e32 v1, v1, v1
	v_mul_f32_e32 v2, v2, v2
	v_mul_f32_e32 v3, v3, v3
	s_and_b64 vcc, exec, s[0:1]
	s_mov_b32 s67, s14
	s_mov_b32 s38, s28
	s_mov_b64 s[4:5], s[36:37]
	s_mov_b64 s[2:3], s[34:35]
	v_mul_f32_e32 v4, v4, v4
	v_cvt_pk_bf16_f32 v0, v4, v0
	v_cvt_pk_bf16_f32 v1, v1, v2
	v_cvt_pk_bf16_f32 v2, v8, v5
	v_cvt_pk_bf16_f32 v3, v6, v3
	global_store_dwordx4 v[16:17], v[0:3], off offset:256
	s_cbranch_vccz .LBB0_253
	s_waitcnt vmcnt(0)
	v_readlane_b32 s62, v254, 59
	s_cmpk_gt_u32 s41, 0xff
	v_readlane_b32 s55, v254, 57
	v_readlane_b32 s58, v254, 58
	v_readlane_b32 s63, v254, 60
	v_readlane_b32 s59, v255, 1
	s_movk_i32 s66, 0x3000
	v_readlane_b32 s49, v255, 18
	s_cbranch_scc1 .LBB0_260
	s_barrier

.LBB0_312:
	s_and_b64 vcc, exec, s[0:1]
	s_cbranch_vccnz .LBB0_544
	v_bfe_i32 v2, v0, 27, 1
	v_lshlrev_b32_e32 v4, 4, v0
	v_lshrrev_b32_e32 v2, 22, v2
	v_add_u32_e32 v2, v4, v2
	v_and_b32_e32 v2, 0xfffffc00, v2
	v_sub_u32_e32 v2, v4, v2
	v_lshrrev_b32_e32 v3, 4, v2
	v_bitop3_b32 v3, v3, v2, 32 bitop3:0x6c
	v_ashrrev_i32_e32 v2, 31, v2
	v_lshrrev_b32_e32 v2, 26, v2
	v_ashrrev_i32_e32 v1, 31, v0
	v_add_u32_e32 v2, v3, v2
	v_lshrrev_b32_e32 v1, 26, v1
	v_ashrrev_i32_e32 v2, 6, v2
	v_add_u32_e32 v1, v0, v1
	v_mul_i32_i24_e32 v7, 64, v2
	v_ashrrev_i32_e32 v1, 6, v1
	v_sub_u32_e32 v3, v3, v7
	v_lshlrev_b32_e32 v5, 3, v1
	v_lshlrev_b32_e32 v6, 5, v1
	v_ashrrev_i16_sdwa v3, v226, sext(v3) dst_sel:DWORD dst_unused:UNUSED_PAD src0_sel:DWORD src1_sel:BYTE_0
	v_and_b32_e32 v5, -16, v5
	v_and_b32_e32 v6, 32, v6
	v_bfe_i32 v3, v3, 0, 16
	v_add_u32_e32 v5, v2, v5
	v_and_b32_e32 v9, 3, v2
	s_mov_b32 s1, 0xfffe0
	v_add_lshl_u32 v6, v6, v3, 1
	v_lshlrev_b32_e32 v7, 1, v5
	v_lshrrev_b32_e32 v8, 2, v5
	v_and_or_b32 v9, v5, s1, v9
	v_lshl_add_u32 v194, v5, 12, v6
	v_add_u32_e32 v5, 0x2000, v4
	v_ashrrev_i32_e32 v4, 31, v5
	v_lshrrev_b32_e32 v4, 22, v4
	v_and_b32_e32 v7, 24, v7
	v_and_b32_e32 v8, 4, v8
	v_add_u32_e32 v4, v5, v4
	v_or3_b32 v7, v9, v8, v7
	v_ashrrev_i32_e32 v4, 10, v4
	v_lshl_add_u32 v196, v7, 12, v6
	v_mul_i32_i24_e32 v6, 0x400, v4
	v_sub_u32_e32 v5, v5, v6
	v_lshrrev_b32_e32 v6, 4, v5
	v_bitop3_b32 v6, v6, v5, 32 bitop3:0x6c
	v_lshlrev_b32_e32 v5, 3, v4
	v_and_b32_e32 v7, -16, v5
	v_ashrrev_i32_e32 v5, 31, v6
	v_lshrrev_b32_e32 v5, 26, v5
	v_add_u32_e32 v8, v6, v5
	v_ashrrev_i32_e32 v5, 6, v8
	v_and_b32_e32 v8, 0xc0, v8
	s_ashr_i32 s0, s82, 6
	v_add_u32_e32 v7, v5, v7
	v_sub_u32_e32 v6, v6, v8
	v_lshlrev_b32_e32 v9, 5, v4
	v_ashrrev_i16_sdwa v6, v226, sext(v6) dst_sel:DWORD dst_unused:UNUSED_PAD src0_sel:DWORD src1_sel:BYTE_0
	v_lshlrev_b32_e32 v8, 1, v7
	v_lshrrev_b32_e32 v10, 2, v7
	v_and_b32_e32 v11, 3, v5
	s_lshl_b32 s50, s0, 10
	v_and_b32_e32 v9, 32, v9
	v_bfe_i32 v6, v6, 0, 16
	v_and_b32_e32 v8, 24, v8
	v_and_b32_e32 v10, 4, v10
	v_and_or_b32 v11, v7, s1, v11
	s_add_i32 s51, s50, 0
	v_or3_b32 v8, v11, v10, v8
	v_add_lshl_u32 v9, v9, v6, 1
	s_add_i32 m0, s51, 0x10000
	v_lshl_add_u32 v200, v8, 12, v9
	global_load_lds_dwordx4 v196, s[2:3]
	s_add_i32 m0, s51, 0x12000
	s_ashr_i32 s1, s82, 8
	global_load_lds_dwordx4 v200, s[2:3]
	s_mov_b32 m0, s51
	s_add_i32 s62, s51, 0x2000
	v_lshl_add_u32 v198, v7, 12, v9
	global_load_lds_dwordx4 v194, s[4:5]
	s_mov_b32 m0, s62
	s_add_u32 s10, s2, 0x80000
	global_load_lds_dwordx4 v198, s[4:5]
	s_addc_u32 s11, s3, 0
	s_add_i32 m0, s51, 0x14000
	v_mov_b32_e32 v197, v193
	global_load_lds_dwordx4 v196, s[10:11]
	s_add_i32 m0, s51, 0x16000
	v_lshl_add_u64 v[8:9], s[2:3], 0, v[196:197]
	global_load_lds_dwordx4 v200, s[10:11]
	s_add_u32 s10, s4, 0x80000
	s_addc_u32 s11, s5, 0
	s_add_i32 s63, s51, 0x4000
	s_mov_b32 m0, s63
	s_add_i32 s69, s51, 0x6000
	v_mov_b32_e32 v201, v193
	global_load_lds_dwordx4 v194, s[10:11]
	s_mov_b32 m0, s69
	v_lshl_add_u64 v[10:11], s[2:3], 0, v[200:201]
	v_mov_b32_e32 v195, v193
	global_load_lds_dwordx4 v198, s[10:11]
	s_add_i32 m0, s51, 0x18000
	v_lshl_add_u64 v[8:9], v[8:9], 0, s[72:73]
	v_lshl_add_u64 v[12:13], s[4:5], 0, v[194:195]
	v_mov_b32_e32 v199, v193
	global_load_lds_dwordx4 v[8:9], off
	v_lshl_add_u64 v[8:9], v[10:11], 0, s[72:73]
	s_add_i32 m0, s51, 0x1a000
	s_add_i32 s71, s51, 0x8000
	v_lshl_add_u64 v[14:15], s[4:5], 0, v[198:199]
	global_load_lds_dwordx4 v[8:9], off
	v_lshl_add_u64 v[8:9], v[12:13], 0, s[72:73]
	s_mov_b32 m0, s71
	s_add_i32 s75, s51, 0xa000
	global_load_lds_dwordx4 v[8:9], off
	v_lshl_add_u64 v[8:9], v[14:15], 0, s[72:73]
	s_mov_b32 m0, s75
	s_add_u32 s10, s2, 0x80080
	global_load_lds_dwordx4 v[8:9], off
	s_addc_u32 s11, s3, 0
	s_add_i32 m0, s51, 0x1c000
	v_mov_b32_e32 v237, v225
	global_load_lds_dwordx4 v196, s[10:11]
	s_add_i32 m0, s51, 0x1e000
	s_mov_b32 s98, s1
	s_cmp_lg_u32 s1, 1
	global_load_lds_dwordx4 v200, s[10:11]
	s_cbranch_scc1 .LBB0_315
	s_barrier

.LBB0_329:
	v_add_u32_e32 v140, 0x10000, v249
	ds_read_b128 v[128:131], v140
	ds_read_b128 v[132:135], v140 offset:1024
	ds_read_b128 v[136:139], v140 offset:2048
	ds_read_b128 v[140:143], v140 offset:3072
	ds_read_b128 v[144:147], v250
	ds_read_b128 v[148:151], v250 offset:1024
	ds_read_b128 v[152:155], v250 offset:2048
	ds_read_b128 v[156:159], v250 offset:3072
	ds_read_b128 v[160:163], v250 offset:4096
	ds_read_b128 v[164:167], v250 offset:5120
	ds_read_b128 v[168:171], v250 offset:6144
	ds_read_b128 v[172:175], v250 offset:7168
	v_add_u32_e32 v188, 0x14000, v249
	ds_read_b128 v[176:179], v188
	ds_read_b128 v[180:183], v188 offset:1024
	ds_read_b128 v[184:187], v188 offset:2048
	ds_read_b128 v[188:191], v188 offset:3072
	s_add_u32 s2, s0, 0xfff80080
	s_addc_u32 s3, s1, -1
	s_add_i32 s9, 0, 0x10000
	s_cmp_eq_u32 s40, 28
	s_cselect_b32 s5, s53, s3
	s_cselect_b32 s4, s52, s2
	s_cselect_b32 s3, s67, s37
	s_cselect_b32 s2, s66, s36
	v_lshl_add_u64 v[218:219], s[0:1], 0, v[202:203]
	s_add_i32 m0, s51, 0xc000
	s_nop 0
	global_load_lds_dwordx4 v[218:219], off
	v_lshl_add_u64 v[220:221], s[0:1], 0, v[204:205]
	s_add_i32 m0, s51, 0xe000
	s_nop 0
	global_load_lds_dwordx4 v[220:221], off
	s_cmp_eq_u32 s98, 0
	s_cbranch_scc1 .Lawa329w1
	s_waitcnt vmcnt(8)
.Lawa329w1:
	s_waitcnt lgkmcnt(0)
	s_barrier
	s_setprio 1
	v_mfma_f32_16x16x32_bf16 v[124:127], v[128:131], v[144:147], v[124:127]
	v_mfma_f32_16x16x32_bf16 v[120:123], v[136:139], v[144:147], v[120:123]
	v_mfma_f32_16x16x32_bf16 v[108:111], v[128:131], v[152:155], v[108:111]
	v_mfma_f32_16x16x32_bf16 v[104:107], v[136:139], v[152:155], v[104:107]
	v_mfma_f32_16x16x32_bf16 v[92:95], v[128:131], v[160:163], v[92:95]
	v_mfma_f32_16x16x32_bf16 v[88:91], v[136:139], v[160:163], v[88:91]
	v_mfma_f32_16x16x32_bf16 v[76:79], v[128:131], v[168:171], v[76:79]
	v_mfma_f32_16x16x32_bf16 v[72:75], v[136:139], v[168:171], v[72:75]
	v_mfma_f32_16x16x32_bf16 v[124:127], v[132:135], v[148:151], v[124:127]
	v_mfma_f32_16x16x32_bf16 v[120:123], v[140:143], v[148:151], v[120:123]
	v_mfma_f32_16x16x32_bf16 v[108:111], v[132:135], v[156:159], v[108:111]
	v_mfma_f32_16x16x32_bf16 v[104:107], v[140:143], v[156:159], v[104:107]
	v_mfma_f32_16x16x32_bf16 v[92:95], v[132:135], v[164:167], v[92:95]
	v_mfma_f32_16x16x32_bf16 v[88:91], v[140:143], v[164:167], v[88:91]
	v_mfma_f32_16x16x32_bf16 v[76:79], v[132:135], v[172:175], v[76:79]
	v_mfma_f32_16x16x32_bf16 v[72:75], v[140:143], v[172:175], v[72:75]
	v_mfma_f32_16x16x32_bf16 v[116:119], v[176:179], v[144:147], v[116:119]
	v_mfma_f32_16x16x32_bf16 v[112:115], v[184:187], v[144:147], v[112:115]
	v_mfma_f32_16x16x32_bf16 v[100:103], v[176:179], v[152:155], v[100:103]
	v_mfma_f32_16x16x32_bf16 v[96:99], v[184:187], v[152:155], v[96:99]
	v_mfma_f32_16x16x32_bf16 v[84:87], v[176:179], v[160:163], v[84:87]
	v_mfma_f32_16x16x32_bf16 v[80:83], v[184:187], v[160:163], v[80:83]
	v_mfma_f32_16x16x32_bf16 v[68:71], v[176:179], v[168:171], v[68:71]
	v_mfma_f32_16x16x32_bf16 v[64:67], v[184:187], v[168:171], v[64:67]
	v_mfma_f32_16x16x32_bf16 v[116:119], v[180:183], v[148:151], v[116:119]
	v_mfma_f32_16x16x32_bf16 v[112:115], v[188:191], v[148:151], v[112:115]
	v_mfma_f32_16x16x32_bf16 v[100:103], v[180:183], v[156:159], v[100:103]
	v_mfma_f32_16x16x32_bf16 v[96:99], v[188:191], v[156:159], v[96:99]
	v_mfma_f32_16x16x32_bf16 v[84:87], v[180:183], v[164:167], v[84:87]
	v_mfma_f32_16x16x32_bf16 v[80:83], v[188:191], v[164:167], v[80:83]
	v_mfma_f32_16x16x32_bf16 v[68:71], v[180:183], v[172:175], v[68:71]
	v_mfma_f32_16x16x32_bf16 v[64:67], v[188:191], v[172:175], v[64:67]
	s_setprio 0
	s_cmp_lg_u32 s98, 0
	s_cbranch_scc1 .Lawa329w2
	s_waitcnt vmcnt(8)
.Lawa329w2:
	s_barrier
	ds_read_b128 v[144:147], v250 offset:16384
	ds_read_b128 v[148:151], v250 offset:17408
	ds_read_b128 v[152:155], v250 offset:18432
	ds_read_b128 v[156:159], v250 offset:19456
	ds_read_b128 v[160:163], v250 offset:20480
	ds_read_b128 v[164:167], v250 offset:21504
	ds_read_b128 v[168:171], v250 offset:22528
	ds_read_b128 v[172:175], v250 offset:23552
	s_add_i32 s41, 0, 0x14000
	s_add_i32 s9, s9, s50
	v_lshl_add_u64 v[206:207], s[2:3], 0, v[196:197]
	s_mov_b32 m0, s9
	s_nop 0
	global_load_lds_dwordx4 v[206:207], off
	v_lshl_add_u64 v[208:209], s[2:3], 0, v[200:201]
	s_add_i32 m0, s9, 0x2000
	s_nop 0
	global_load_lds_dwordx4 v[208:209], off
	s_mov_b32 m0, s51
	v_lshl_add_u64 v[210:211], s[4:5], 0, v[194:195]
	global_load_lds_dwordx4 v[210:211], off
	v_lshl_add_u64 v[212:213], s[4:5], 0, v[198:199]
	s_mov_b32 m0, s62
	s_nop 0
	global_load_lds_dwordx4 v[212:213], off
	s_add_u32 s46, s2, 0x80000
	s_addc_u32 s47, s3, 0
	s_add_i32 s9, s41, s50
	v_lshl_add_u64 v[218:219], s[46:47], 0, v[196:197]
	s_mov_b32 m0, s9
	s_nop 0
	global_load_lds_dwordx4 v[218:219], off
	v_lshl_add_u64 v[220:221], s[46:47], 0, v[200:201]
	s_add_i32 m0, s9, 0x2000
	s_nop 0
	global_load_lds_dwordx4 v[220:221], off
	s_cmp_eq_u32 s98, 0
	s_cbranch_scc1 .Lawa329w3
	s_waitcnt vmcnt(8)
.Lawa329w3:
	s_waitcnt lgkmcnt(0)
	s_barrier
	s_setprio 1
	v_mfma_f32_16x16x32_bf16 v[60:63], v[128:131], v[144:147], v[60:63]
	v_mfma_f32_16x16x32_bf16 v[56:59], v[136:139], v[144:147], v[56:59]
	v_mfma_f32_16x16x32_bf16 v[44:47], v[128:131], v[152:155], v[44:47]
	v_mfma_f32_16x16x32_bf16 v[40:43], v[136:139], v[152:155], v[40:43]
	v_mfma_f32_16x16x32_bf16 v[28:31], v[128:131], v[160:163], v[28:31]
	v_mfma_f32_16x16x32_bf16 v[24:27], v[136:139], v[160:163], v[24:27]
	v_mfma_f32_16x16x32_bf16 v[12:15], v[128:131], v[168:171], v[12:15]
	v_mfma_f32_16x16x32_bf16 v[8:11], v[136:139], v[168:171], v[8:11]
	v_mfma_f32_16x16x32_bf16 v[60:63], v[132:135], v[148:151], v[60:63]
	v_mfma_f32_16x16x32_bf16 v[56:59], v[140:143], v[148:151], v[56:59]
	v_mfma_f32_16x16x32_bf16 v[44:47], v[132:135], v[156:159], v[44:47]
	v_mfma_f32_16x16x32_bf16 v[40:43], v[140:143], v[156:159], v[40:43]
	v_mfma_f32_16x16x32_bf16 v[28:31], v[132:135], v[164:167], v[28:31]
	v_mfma_f32_16x16x32_bf16 v[24:27], v[140:143], v[164:167], v[24:27]
	v_mfma_f32_16x16x32_bf16 v[12:15], v[132:135], v[172:175], v[12:15]
	v_mfma_f32_16x16x32_bf16 v[8:11], v[140:143], v[172:175], v[8:11]
	v_mfma_f32_16x16x32_bf16 v[52:55], v[176:179], v[144:147], v[52:55]
	v_mfma_f32_16x16x32_bf16 v[48:51], v[184:187], v[144:147], v[48:51]
	v_mfma_f32_16x16x32_bf16 v[36:39], v[176:179], v[152:155], v[36:39]
	v_mfma_f32_16x16x32_bf16 v[32:35], v[184:187], v[152:155], v[32:35]
	v_mfma_f32_16x16x32_bf16 v[20:23], v[176:179], v[160:163], v[20:23]
	v_mfma_f32_16x16x32_bf16 v[16:19], v[184:187], v[160:163], v[16:19]
	v_mfma_f32_16x16x32_bf16 v[4:7], v[176:179], v[168:171], v[4:7]
	v_mfma_f32_16x16x32_bf16 v[0:3], v[184:187], v[168:171], v[0:3]
	v_mfma_f32_16x16x32_bf16 v[52:55], v[180:183], v[148:151], v[52:55]
	v_mfma_f32_16x16x32_bf16 v[48:51], v[188:191], v[148:151], v[48:51]
	v_mfma_f32_16x16x32_bf16 v[36:39], v[180:183], v[156:159], v[36:39]
	v_mfma_f32_16x16x32_bf16 v[32:35], v[188:191], v[156:159], v[32:35]
	v_mfma_f32_16x16x32_bf16 v[20:23], v[180:183], v[164:167], v[20:23]
	v_mfma_f32_16x16x32_bf16 v[16:19], v[188:191], v[164:167], v[16:19]
	v_mfma_f32_16x16x32_bf16 v[4:7], v[180:183], v[172:175], v[4:7]
	v_mfma_f32_16x16x32_bf16 v[0:3], v[188:191], v[172:175], v[0:3]
	s_setprio 0
	s_cmp_lg_u32 s98, 0
	s_cbranch_scc1 .Lawa329w4
	s_waitcnt vmcnt(8)
.Lawa329w4:
	s_barrier
	v_add_u32_e32 v140, 0x18000, v249
	ds_read_b128 v[128:131], v140
	ds_read_b128 v[132:135], v140 offset:1024
	ds_read_b128 v[136:139], v140 offset:2048
	ds_read_b128 v[140:143], v140 offset:3072
	ds_read_b128 v[144:147], v250 offset:32768
	ds_read_b128 v[148:151], v250 offset:33792
	ds_read_b128 v[152:155], v250 offset:34816
	ds_read_b128 v[156:159], v250 offset:35840
	ds_read_b128 v[160:163], v250 offset:36864
	ds_read_b128 v[164:167], v250 offset:37888
	ds_read_b128 v[168:171], v250 offset:38912
	ds_read_b128 v[172:175], v250 offset:39936
	v_add_u32_e32 v188, 0x1c000, v249
	ds_read_b128 v[176:179], v188
	ds_read_b128 v[180:183], v188 offset:1024
	ds_read_b128 v[184:187], v188 offset:2048
	ds_read_b128 v[188:191], v188 offset:3072
	s_add_i32 s9, 0, 0x18000
	s_add_u32 s4, s4, 0x80000
	s_addc_u32 s5, s5, 0
	s_mov_b32 m0, s63
	v_lshl_add_u64 v[218:219], s[4:5], 0, v[194:195]
	global_load_lds_dwordx4 v[218:219], off
	v_lshl_add_u64 v[220:221], s[4:5], 0, v[198:199]
	s_mov_b32 m0, s69
	s_nop 0
	global_load_lds_dwordx4 v[220:221], off
	s_cmp_eq_u32 s98, 0
	s_cbranch_scc1 .Lawa329w5
	s_waitcnt vmcnt(8)

.Lawa329w6:
	s_barrier
	ds_read_b128 v[144:147], v250 offset:49152
	ds_read_b128 v[148:151], v250 offset:50176
	ds_read_b128 v[152:155], v250 offset:51200
	ds_read_b128 v[156:159], v250 offset:52224
	ds_read_b128 v[160:163], v250 offset:53248
	ds_read_b128 v[164:167], v250 offset:54272
	ds_read_b128 v[168:171], v250 offset:55296
	ds_read_b128 v[172:175], v250 offset:56320
	s_add_i32 s4, 0, 0x1c000
	s_add_i32 s5, s9, s50
	v_lshl_add_u64 v[206:207], v[206:207], 0, s[72:73]
	s_mov_b32 m0, s5
	s_nop 0
	global_load_lds_dwordx4 v[206:207], off
	v_lshl_add_u64 v[206:207], v[208:209], 0, s[72:73]
	s_add_i32 m0, s5, 0x2000
	s_nop 0
	global_load_lds_dwordx4 v[206:207], off
	s_mov_b32 m0, s71
	v_lshl_add_u64 v[206:207], v[210:211], 0, s[72:73]
	global_load_lds_dwordx4 v[206:207], off
	v_lshl_add_u64 v[206:207], v[212:213], 0, s[72:73]
	s_mov_b32 m0, s75
	s_nop 0
	global_load_lds_dwordx4 v[206:207], off
	s_add_u32 s2, s2, 0x80080
	s_addc_u32 s3, s3, 0
	s_add_i32 s4, s4, s50
	v_lshl_add_u64 v[218:219], s[2:3], 0, v[196:197]
	s_mov_b32 m0, s4
	s_nop 0
	global_load_lds_dwordx4 v[218:219], off
	v_lshl_add_u64 v[220:221], s[2:3], 0, v[200:201]
	s_add_i32 m0, s4, 0x2000
	s_nop 0
	global_load_lds_dwordx4 v[220:221], off
	s_cmp_eq_u32 s98, 0
	s_cbranch_scc1 .Lawa329w7
	s_waitcnt vmcnt(8)

.Lawa329w8:
	s_add_i32 s40, s40, 2
	s_add_u32 s0, s0, 0x100
	s_addc_u32 s1, s1, 0
	s_add_u32 s36, s36, 0x100
	s_addc_u32 s37, s37, 0
	s_cmp_gt_u32 s40, 29
	s_barrier
	s_cbranch_scc0 .LBB0_329
	v_mov_b32 v128, v248
	s_cmp_gt_u32 s38, 1
	v_and_b32_e32 v246, 15, v128
	v_ashrrev_i32_e32 v247, 4, v128
	s_mov_b64 s[0:1], -1
	s_cbranch_scc0 .LBB0_413
	s_and_b32 s4, s39, 3
	s_cmp_lg_u32 s38, 2
	s_cbranch_scc0 .LBB0_400
	s_lshl_b32 s40, s49, 8
	v_or_b32_e32 v128, s78, v246
	v_add_u32_e32 v134, s40, v128
	v_min_i32_e32 v130, 0x2000, v134
	v_lshlrev_b32_e32 v130, 8, v130
	v_add_lshl_u32 v206, v247, s85, 2
	v_readlane_b32 s0, v251, 61
	v_and_b32_e32 v192, 0x7cf00, v130
	v_or_b32_e32 v130, 16, v134
	v_ashrrev_i32_e32 v207, 31, v206
	v_readlane_b32 s1, v251, 62
	v_min_i32_e32 v130, 0x2000, v130
	v_or_b32_e32 v132, 32, v134
	v_lshl_add_u64 v[128:129], v[206:207], 2, s[0:1]
	v_lshlrev_b32_e32 v130, 8, v130
	v_min_i32_e32 v132, 0x2000, v132
	v_lshl_add_u64 v[210:211], v[128:129], 0, v[192:193]
	v_and_b32_e32 v192, 0x7ff00, v130
	v_lshlrev_b32_e32 v132, 8, v132
	v_lshl_add_u64 v[130:131], v[128:129], 0, v[192:193]
	v_and_b32_e32 v192, 0x7ff00, v132
	global_load_dwordx4 v[188:191], v[210:211], off offset:128
	global_load_dwordx4 v[176:179], v[130:131], off
	v_lshl_add_u64 v[132:133], v[128:129], 0, v[192:193]
	global_load_dwordx4 v[180:183], v[130:131], off offset:128
	global_load_dwordx4 v[168:171], v[132:133], off
	v_or_b32_e32 v130, 48, v134
	v_min_i32_e32 v130, 0x2000, v130
	v_lshlrev_b32_e32 v130, 8, v130
	v_and_b32_e32 v192, 0x7ff00, v130
	v_lshl_add_u64 v[130:131], v[128:129], 0, v[192:193]
	global_load_dwordx4 v[172:175], v[132:133], off offset:128
	global_load_dwordx4 v[160:163], v[130:131], off
	v_add_u32_e32 v132, 0x80, v134
	v_min_i32_e32 v132, 0x2000, v132
	v_lshlrev_b32_e32 v132, 8, v132
	v_and_b32_e32 v192, 0x7ff00, v132
	v_lshl_add_u64 v[132:133], v[128:129], 0, v[192:193]
	global_load_dwordx4 v[164:167], v[130:131], off offset:128
	global_load_dwordx4 v[152:155], v[132:133], off
	v_add_u32_e32 v130, 0x90, v134
	v_min_i32_e32 v130, 0x2000, v130
	v_lshlrev_b32_e32 v130, 8, v130
	v_and_b32_e32 v192, 0x7ff00, v130
	v_lshl_add_u64 v[130:131], v[128:129], 0, v[192:193]
	global_load_dwordx4 v[156:159], v[132:133], off offset:128
	global_load_dwordx4 v[144:147], v[130:131], off
	v_add_u32_e32 v132, 0xa0, v134
	v_min_i32_e32 v132, 0x2000, v132
	v_lshlrev_b32_e32 v132, 8, v132
	v_and_b32_e32 v192, 0x7ff00, v132
	v_lshl_add_u64 v[132:133], v[128:129], 0, v[192:193]
	global_load_dwordx4 v[148:151], v[130:131], off offset:128
	global_load_dwordx4 v[136:139], v[132:133], off
	v_add_u32_e32 v130, 0xb0, v134
	v_min_i32_e32 v130, 0x2000, v130
	v_lshlrev_b32_e32 v130, 8, v130
	v_and_b32_e32 v192, 0x7ff00, v130
	v_lshl_add_u64 v[128:129], v[128:129], 0, v[192:193]
	global_load_dwordx4 v[140:143], v[132:133], off offset:128
	s_nop 0
	global_load_dwordx4 v[132:135], v[128:129], off
	s_nop 0
	global_load_dwordx4 v[128:131], v[128:129], off offset:128
	s_add_i32 s2, s40, s78
	v_or_b32_e32 v208, s2, v246
	v_mov_b32_e32 v184, 1.0
	v_cmp_gt_i32_e32 vcc, s33, v208
	v_mov_b32_e32 v185, v184
	v_mov_b32_e32 v186, v184
	v_mov_b32_e32 v187, v184
	s_and_saveexec_b64 s[0:1], vcc
	s_cbranch_execz .LBB0_334
	global_load_dwordx4 v[184:187], v[210:211], off
